# compress k-loop software-pipelined; sb softplus in log2 domain + K ping-pong; phase-3 bias table built with batched loads
# speedup vs baseline: 1.0264x; 1.0139x over previous
.LBB0_248:
	s_and_b64 vcc, exec, s[0:1]
	s_cbranch_vccz .LBB0_258
	s_cmp_gt_i32 s35, 1
	s_mov_b64 s[0:1], -1
	s_cbranch_scc0 .LBB0_386
	s_cmp_gt_i32 s35, 2
	s_cbranch_scc0 .LBB0_362
	v_readlane_b32 s0, v254, 31
	v_readlane_b32 s4, v254, 35
	v_readlane_b32 s5, v254, 36
	v_readlane_b32 s6, v254, 37
	v_readlane_b32 s7, v254, 38
	v_readlane_b32 s2, v254, 33
	s_mov_b64 s[6:7], s[4:5]
	s_waitcnt vmcnt(0)
	v_mov_b32_e32 v2, v186
	s_movk_i32 s0, 0x5300
	v_readlane_b32 s8, v254, 39
	v_readlane_b32 s9, v254, 40
	v_readlane_b32 s1, v254, 32
	v_readfirstlane_b32 s2, v2
	v_cmp_gt_i32_e32 vcc, s0, v2
	v_readlane_b32 s3, v254, 34
	v_readlane_b32 s10, v254, 41
	v_readlane_b32 s11, v254, 42
	v_readlane_b32 s12, v254, 43
	v_readlane_b32 s13, v254, 44
	v_readlane_b32 s14, v254, 45
	v_readlane_b32 s15, v254, 46
	s_and_saveexec_b64 s[8:9], vcc
	s_cbranch_execz .LBB0_259
	s_add_u32 s10, s54, 0x2d0a7fc0
	s_addc_u32 s11, s55, 0
	global_load_dwordx4 v[40:43], v65, s[10:11]
	global_load_dwordx4 v[44:47], v65, s[10:11] offset:16
	s_mov_b32 s3, 0x40851592
	s_mov_b32 s12, 0x3fb8aa3b
	s_movk_i32 s13, 0x220
	v_mov_b32_e32 v9, v186
	v_lshlrev_b32_e32 v48, 2, v9
	v_cmp_gt_i32_e32 vcc, 0x820, v9
	v_add_u32_e32 v10, 0xfffff7e0, v9
	s_nop 1
	v_cndmask_b32_e32 v10, v10, v9, vcc
	v_cmp_gt_i32_e64 s[4:5], s13, v10
	v_cmp_lt_i32_e64 s[0:1], 31, v10
	s_or_b64 s[4:5], vcc, s[4:5]
	s_and_b64 s[16:17], s[0:1], s[4:5]
	v_subrev_u32_e32 v11, 32, v10
	v_cmp_lt_u32_e64 s[30:31], 15, v11
	v_cvt_f32_u32_e32 v1, v11
	v_mul_f32_e32 v1, 0x3d800000, v1
	v_cmp_gt_f32_e32 vcc, s33, v1
	s_nop 1
	v_cndmask_b32_e64 v4, 0, 32, vcc
	v_ldexp_f32 v1, v1, v4
	v_log_f32_e32 v1, v1
	v_cndmask_b32_e32 v4, 0, v192, vcc
	v_mul_f32_e32 v5, 0x3f317217, v1
	v_fma_f32 v5, v1, s78, -v5
	v_fmac_f32_e32 v5, 0x3377d1cf, v1
	v_fmac_f32_e32 v5, 0x3f317217, v1
	v_cmp_lt_f32_e64 vcc, |v1|, s79
	s_nop 1
	v_cndmask_b32_e32 v1, v1, v5, vcc
	v_sub_f32_e32 v1, v1, v4
	v_div_scale_f32 v4, s[14:15], s3, s3, v1
	v_rcp_f32_e32 v5, v4
	v_div_scale_f32 v6, vcc, v1, s3, v1
	v_fma_f32 v7, -v4, v5, 1.0
	v_fmac_f32_e32 v5, v7, v5
	v_mul_f32_e32 v7, v6, v5
	v_fma_f32 v8, -v4, v7, v6
	v_fmac_f32_e32 v7, v8, v5
	v_fma_f32 v4, -v4, v7, v6
	v_div_fmas_f32 v4, v4, v5, v7
	v_div_fixup_f32 v1, v4, s3, v1
	v_mul_f32_e32 v1, 0x41800000, v1
	v_cvt_i32_f32_e32 v1, v1
	v_min_i32_e32 v1, 15, v1
	v_add_u32_e32 v1, 16, v1
	v_cndmask_b32_e64 v1, v11, v1, s[30:31]
	v_lshlrev_b32_e32 v54, 5, v1
	s_mov_b64 exec, s[16:17]
	global_load_dwordx4 v[66:69], v54, s[6:7]
	global_load_dwordx4 v[70:73], v54, s[6:7] offset:16
	s_mov_b64 exec, -1
	v_add_u32_e32 v9, 512, v186
	v_lshlrev_b32_e32 v49, 2, v9
	v_cmp_gt_i32_e32 vcc, 0x820, v9
	v_add_u32_e32 v10, 0xfffff7e0, v9
	s_nop 1
	v_cndmask_b32_e32 v10, v10, v9, vcc
	v_cmp_gt_i32_e64 s[4:5], s13, v10
	v_cmp_lt_i32_e64 s[0:1], 31, v10
	s_or_b64 s[4:5], vcc, s[4:5]
	s_and_b64 s[18:19], s[0:1], s[4:5]
	v_subrev_u32_e32 v11, 32, v10
	v_cmp_lt_u32_e64 s[30:31], 15, v11
	v_cvt_f32_u32_e32 v1, v11
	v_mul_f32_e32 v1, 0x3d800000, v1
	v_cmp_gt_f32_e32 vcc, s33, v1
	s_nop 1
	v_cndmask_b32_e64 v4, 0, 32, vcc
	v_ldexp_f32 v1, v1, v4
	v_log_f32_e32 v1, v1
	v_cndmask_b32_e32 v4, 0, v192, vcc
	v_mul_f32_e32 v5, 0x3f317217, v1
	v_fma_f32 v5, v1, s78, -v5
	v_fmac_f32_e32 v5, 0x3377d1cf, v1
	v_fmac_f32_e32 v5, 0x3f317217, v1
	v_cmp_lt_f32_e64 vcc, |v1|, s79
	s_nop 1
	v_cndmask_b32_e32 v1, v1, v5, vcc
	v_sub_f32_e32 v1, v1, v4
	v_div_scale_f32 v4, s[14:15], s3, s3, v1
	v_rcp_f32_e32 v5, v4
	v_div_scale_f32 v6, vcc, v1, s3, v1
	v_fma_f32 v7, -v4, v5, 1.0
	v_fmac_f32_e32 v5, v7, v5
	v_mul_f32_e32 v7, v6, v5
	v_fma_f32 v8, -v4, v7, v6
	v_fmac_f32_e32 v7, v8, v5
	v_fma_f32 v4, -v4, v7, v6
	v_div_fmas_f32 v4, v4, v5, v7
	v_div_fixup_f32 v1, v4, s3, v1
	v_mul_f32_e32 v1, 0x41800000, v1
	v_cvt_i32_f32_e32 v1, v1
	v_min_i32_e32 v1, 15, v1
	v_add_u32_e32 v1, 16, v1
	v_cndmask_b32_e64 v1, v11, v1, s[30:31]
	v_lshlrev_b32_e32 v55, 5, v1
	s_mov_b64 exec, s[18:19]
	global_load_dwordx4 v[74:77], v55, s[6:7]
	global_load_dwordx4 v[78:81], v55, s[6:7] offset:16
	s_mov_b64 exec, -1
	v_add_u32_e32 v9, 1024, v186
	v_lshlrev_b32_e32 v50, 2, v9
	v_cmp_gt_i32_e32 vcc, 0x820, v9
	v_add_u32_e32 v10, 0xfffff7e0, v9
	s_nop 1
	v_cndmask_b32_e32 v10, v10, v9, vcc
	v_cmp_gt_i32_e64 s[4:5], s13, v10
	v_cmp_lt_i32_e64 s[0:1], 31, v10
	s_or_b64 s[4:5], vcc, s[4:5]
	s_and_b64 s[20:21], s[0:1], s[4:5]
	v_subrev_u32_e32 v11, 32, v10
	v_cmp_lt_u32_e64 s[30:31], 15, v11
	v_cvt_f32_u32_e32 v1, v11
	v_mul_f32_e32 v1, 0x3d800000, v1
	v_cmp_gt_f32_e32 vcc, s33, v1
	s_nop 1
	v_cndmask_b32_e64 v4, 0, 32, vcc
	v_ldexp_f32 v1, v1, v4
	v_log_f32_e32 v1, v1
	v_cndmask_b32_e32 v4, 0, v192, vcc
	v_mul_f32_e32 v5, 0x3f317217, v1
	v_fma_f32 v5, v1, s78, -v5
	v_fmac_f32_e32 v5, 0x3377d1cf, v1
	v_fmac_f32_e32 v5, 0x3f317217, v1
	v_cmp_lt_f32_e64 vcc, |v1|, s79
	s_nop 1
	v_cndmask_b32_e32 v1, v1, v5, vcc
	v_sub_f32_e32 v1, v1, v4
	v_div_scale_f32 v4, s[14:15], s3, s3, v1
	v_rcp_f32_e32 v5, v4
	v_div_scale_f32 v6, vcc, v1, s3, v1
	v_fma_f32 v7, -v4, v5, 1.0
	v_fmac_f32_e32 v5, v7, v5
	v_mul_f32_e32 v7, v6, v5
	v_fma_f32 v8, -v4, v7, v6
	v_fmac_f32_e32 v7, v8, v5
	v_fma_f32 v4, -v4, v7, v6
	v_div_fmas_f32 v4, v4, v5, v7
	v_div_fixup_f32 v1, v4, s3, v1
	v_mul_f32_e32 v1, 0x41800000, v1
	v_cvt_i32_f32_e32 v1, v1
	v_min_i32_e32 v1, 15, v1
	v_add_u32_e32 v1, 16, v1
	v_cndmask_b32_e64 v1, v11, v1, s[30:31]
	v_lshlrev_b32_e32 v56, 5, v1
	s_mov_b64 exec, s[20:21]
	global_load_dwordx4 v[82:85], v56, s[6:7]
	global_load_dwordx4 v[86:89], v56, s[6:7] offset:16
	s_mov_b64 exec, -1
	v_add_u32_e32 v9, 1536, v186
	v_lshlrev_b32_e32 v51, 2, v9
	v_cmp_gt_i32_e32 vcc, 0x820, v9
	v_add_u32_e32 v10, 0xfffff7e0, v9
	s_nop 1
	v_cndmask_b32_e32 v10, v10, v9, vcc
	v_cmp_gt_i32_e64 s[4:5], s13, v10
	v_cmp_lt_i32_e64 s[0:1], 31, v10
	s_or_b64 s[4:5], vcc, s[4:5]
	s_and_b64 s[22:23], s[0:1], s[4:5]
	v_subrev_u32_e32 v11, 32, v10
	v_cmp_lt_u32_e64 s[30:31], 15, v11
	v_cvt_f32_u32_e32 v1, v11
	v_mul_f32_e32 v1, 0x3d800000, v1
	v_cmp_gt_f32_e32 vcc, s33, v1
	s_nop 1
	v_cndmask_b32_e64 v4, 0, 32, vcc
	v_ldexp_f32 v1, v1, v4
	v_log_f32_e32 v1, v1
	v_cndmask_b32_e32 v4, 0, v192, vcc
	v_mul_f32_e32 v5, 0x3f317217, v1
	v_fma_f32 v5, v1, s78, -v5
	v_fmac_f32_e32 v5, 0x3377d1cf, v1
	v_fmac_f32_e32 v5, 0x3f317217, v1
	v_cmp_lt_f32_e64 vcc, |v1|, s79
	s_nop 1
	v_cndmask_b32_e32 v1, v1, v5, vcc
	v_sub_f32_e32 v1, v1, v4
	v_div_scale_f32 v4, s[14:15], s3, s3, v1
	v_rcp_f32_e32 v5, v4
	v_div_scale_f32 v6, vcc, v1, s3, v1
	v_fma_f32 v7, -v4, v5, 1.0
	v_fmac_f32_e32 v5, v7, v5
	v_mul_f32_e32 v7, v6, v5
	v_fma_f32 v8, -v4, v7, v6
	v_fmac_f32_e32 v7, v8, v5
	v_fma_f32 v4, -v4, v7, v6
	v_div_fmas_f32 v4, v4, v5, v7
	v_div_fixup_f32 v1, v4, s3, v1
	v_mul_f32_e32 v1, 0x41800000, v1
	v_cvt_i32_f32_e32 v1, v1
	v_min_i32_e32 v1, 15, v1
	v_add_u32_e32 v1, 16, v1
	v_cndmask_b32_e64 v1, v11, v1, s[30:31]
	v_lshlrev_b32_e32 v57, 5, v1
	s_mov_b64 exec, s[22:23]
	global_load_dwordx4 v[90:93], v57, s[6:7]
	global_load_dwordx4 v[94:97], v57, s[6:7] offset:16
	s_mov_b64 exec, -1
	v_add_u32_e32 v9, 2048, v186
	v_lshlrev_b32_e32 v52, 2, v9
	v_cmp_gt_i32_e32 vcc, 0x820, v9
	v_add_u32_e32 v10, 0xfffff7e0, v9
	s_nop 1
	v_cndmask_b32_e32 v10, v10, v9, vcc
	v_cmp_gt_i32_e64 s[4:5], s13, v10
	v_cmp_lt_i32_e64 s[0:1], 31, v10
	s_or_b64 s[4:5], vcc, s[4:5]
	s_and_b64 s[24:25], s[0:1], s[4:5]
	v_subrev_u32_e32 v11, 32, v10
	v_cmp_lt_u32_e64 s[30:31], 15, v11
	v_cvt_f32_u32_e32 v1, v11
	v_mul_f32_e32 v1, 0x3d800000, v1
	v_cmp_gt_f32_e32 vcc, s33, v1
	s_nop 1
	v_cndmask_b32_e64 v4, 0, 32, vcc
	v_ldexp_f32 v1, v1, v4
	v_log_f32_e32 v1, v1
	v_cndmask_b32_e32 v4, 0, v192, vcc
	v_mul_f32_e32 v5, 0x3f317217, v1
	v_fma_f32 v5, v1, s78, -v5
	v_fmac_f32_e32 v5, 0x3377d1cf, v1
	v_fmac_f32_e32 v5, 0x3f317217, v1
	v_cmp_lt_f32_e64 vcc, |v1|, s79
	s_nop 1
	v_cndmask_b32_e32 v1, v1, v5, vcc
	v_sub_f32_e32 v1, v1, v4
	v_div_scale_f32 v4, s[14:15], s3, s3, v1
	v_rcp_f32_e32 v5, v4
	v_div_scale_f32 v6, vcc, v1, s3, v1
	v_fma_f32 v7, -v4, v5, 1.0
	v_fmac_f32_e32 v5, v7, v5
	v_mul_f32_e32 v7, v6, v5
	v_fma_f32 v8, -v4, v7, v6
	v_fmac_f32_e32 v7, v8, v5
	v_fma_f32 v4, -v4, v7, v6
	v_div_fmas_f32 v4, v4, v5, v7
	v_div_fixup_f32 v1, v4, s3, v1
	v_mul_f32_e32 v1, 0x41800000, v1
	v_cvt_i32_f32_e32 v1, v1
	v_min_i32_e32 v1, 15, v1
	v_add_u32_e32 v1, 16, v1
	v_cndmask_b32_e64 v1, v11, v1, s[30:31]
	v_lshlrev_b32_e32 v58, 5, v1
	s_mov_b64 exec, s[24:25]
	global_load_dwordx4 v[98:101], v58, s[6:7]
	global_load_dwordx4 v[102:105], v58, s[6:7] offset:16
	s_mov_b64 exec, -1
	v_add_u32_e32 v9, 2560, v186
	v_lshlrev_b32_e32 v53, 2, v9
	s_movk_i32 s4, 0xa60
	v_cmp_gt_u32_e64 s[28:29], s4, v9
	v_cmp_gt_i32_e32 vcc, 0x820, v9
	v_add_u32_e32 v10, 0xfffff7e0, v9
	s_nop 1
	v_cndmask_b32_e32 v10, v10, v9, vcc
	v_cmp_gt_i32_e64 s[4:5], s13, v10
	v_cmp_lt_i32_e64 s[0:1], 31, v10
	s_or_b64 s[4:5], vcc, s[4:5]
	s_and_b64 s[26:27], s[0:1], s[4:5]
	s_and_b64 s[26:27], s[26:27], s[28:29]
	v_subrev_u32_e32 v11, 32, v10
	v_cmp_lt_u32_e64 s[30:31], 15, v11
	v_cvt_f32_u32_e32 v1, v11
	v_mul_f32_e32 v1, 0x3d800000, v1
	v_cmp_gt_f32_e32 vcc, s33, v1
	s_nop 1
	v_cndmask_b32_e64 v4, 0, 32, vcc
	v_ldexp_f32 v1, v1, v4
	v_log_f32_e32 v1, v1
	v_cndmask_b32_e32 v4, 0, v192, vcc
	v_mul_f32_e32 v5, 0x3f317217, v1
	v_fma_f32 v5, v1, s78, -v5
	v_fmac_f32_e32 v5, 0x3377d1cf, v1
	v_fmac_f32_e32 v5, 0x3f317217, v1
	v_cmp_lt_f32_e64 vcc, |v1|, s79
	s_nop 1
	v_cndmask_b32_e32 v1, v1, v5, vcc
	v_sub_f32_e32 v1, v1, v4
	v_div_scale_f32 v4, s[14:15], s3, s3, v1
	v_rcp_f32_e32 v5, v4
	v_div_scale_f32 v6, vcc, v1, s3, v1
	v_fma_f32 v7, -v4, v5, 1.0
	v_fmac_f32_e32 v5, v7, v5
	v_mul_f32_e32 v7, v6, v5
	v_fma_f32 v8, -v4, v7, v6
	v_fmac_f32_e32 v7, v8, v5
	v_fma_f32 v4, -v4, v7, v6
	v_div_fmas_f32 v4, v4, v5, v7
	v_div_fixup_f32 v1, v4, s3, v1
	v_mul_f32_e32 v1, 0x41800000, v1
	v_cvt_i32_f32_e32 v1, v1
	v_min_i32_e32 v1, 15, v1
	v_add_u32_e32 v1, 16, v1
	v_cndmask_b32_e64 v1, v11, v1, s[30:31]
	v_lshlrev_b32_e32 v59, 5, v1
	s_mov_b64 exec, s[26:27]
	global_load_dwordx4 v[106:109], v59, s[6:7]
	global_load_dwordx4 v[110:113], v59, s[6:7] offset:16
	s_mov_b64 exec, -1
	s_waitcnt vmcnt(0)
	v_fma_f32 v66, v66, s12, -v40
	v_fma_f32 v67, v67, s12, -v41
	v_fma_f32 v68, v68, s12, -v42
	v_fma_f32 v69, v69, s12, -v43
	v_fma_f32 v70, v70, s12, -v44
	v_fma_f32 v71, v71, s12, -v45
	v_fma_f32 v72, v72, s12, -v46
	v_fma_f32 v73, v73, s12, -v47
	v_cndmask_b32_e64 v66, v191, v66, s[16:17]
	v_cndmask_b32_e64 v67, v191, v67, s[16:17]
	v_cndmask_b32_e64 v68, v191, v68, s[16:17]
	v_cndmask_b32_e64 v69, v191, v69, s[16:17]
	v_cndmask_b32_e64 v70, v191, v70, s[16:17]
	v_cndmask_b32_e64 v71, v191, v71, s[16:17]
	v_cndmask_b32_e64 v72, v191, v72, s[16:17]
	v_cndmask_b32_e64 v73, v191, v73, s[16:17]
	v_add_u32_e32 v60, 0xa600, v48
	ds_write_b32 v48, v66
	ds_write_b32 v48, v67 offset:10624
	ds_write_b32 v48, v68 offset:21248
	ds_write_b32 v48, v69 offset:31872
	ds_write_b32 v60, v70
	ds_write_b32 v60, v71 offset:10624
	ds_write_b32 v60, v72 offset:21248
	ds_write_b32 v60, v73 offset:31872
	v_fma_f32 v74, v74, s12, -v40
	v_fma_f32 v75, v75, s12, -v41
	v_fma_f32 v76, v76, s12, -v42
	v_fma_f32 v77, v77, s12, -v43
	v_fma_f32 v78, v78, s12, -v44
	v_fma_f32 v79, v79, s12, -v45
	v_fma_f32 v80, v80, s12, -v46
	v_fma_f32 v81, v81, s12, -v47
	v_cndmask_b32_e64 v74, v191, v74, s[18:19]
	v_cndmask_b32_e64 v75, v191, v75, s[18:19]
	v_cndmask_b32_e64 v76, v191, v76, s[18:19]
	v_cndmask_b32_e64 v77, v191, v77, s[18:19]
	v_cndmask_b32_e64 v78, v191, v78, s[18:19]
	v_cndmask_b32_e64 v79, v191, v79, s[18:19]
	v_cndmask_b32_e64 v80, v191, v80, s[18:19]
	v_cndmask_b32_e64 v81, v191, v81, s[18:19]
	v_add_u32_e32 v60, 0xa600, v49
	ds_write_b32 v49, v74
	ds_write_b32 v49, v75 offset:10624
	ds_write_b32 v49, v76 offset:21248
	ds_write_b32 v49, v77 offset:31872
	ds_write_b32 v60, v78
	ds_write_b32 v60, v79 offset:10624
	ds_write_b32 v60, v80 offset:21248
	ds_write_b32 v60, v81 offset:31872
	v_fma_f32 v82, v82, s12, -v40
	v_fma_f32 v83, v83, s12, -v41
	v_fma_f32 v84, v84, s12, -v42
	v_fma_f32 v85, v85, s12, -v43
	v_fma_f32 v86, v86, s12, -v44
	v_fma_f32 v87, v87, s12, -v45
	v_fma_f32 v88, v88, s12, -v46
	v_fma_f32 v89, v89, s12, -v47
	v_cndmask_b32_e64 v82, v191, v82, s[20:21]
	v_cndmask_b32_e64 v83, v191, v83, s[20:21]
	v_cndmask_b32_e64 v84, v191, v84, s[20:21]
	v_cndmask_b32_e64 v85, v191, v85, s[20:21]
	v_cndmask_b32_e64 v86, v191, v86, s[20:21]
	v_cndmask_b32_e64 v87, v191, v87, s[20:21]
	v_cndmask_b32_e64 v88, v191, v88, s[20:21]
	v_cndmask_b32_e64 v89, v191, v89, s[20:21]
	v_add_u32_e32 v60, 0xa600, v50
	ds_write_b32 v50, v82
	ds_write_b32 v50, v83 offset:10624
	ds_write_b32 v50, v84 offset:21248
	ds_write_b32 v50, v85 offset:31872
	ds_write_b32 v60, v86
	ds_write_b32 v60, v87 offset:10624
	ds_write_b32 v60, v88 offset:21248
	ds_write_b32 v60, v89 offset:31872
	v_fma_f32 v90, v90, s12, -v40
	v_fma_f32 v91, v91, s12, -v41
	v_fma_f32 v92, v92, s12, -v42
	v_fma_f32 v93, v93, s12, -v43
	v_fma_f32 v94, v94, s12, -v44
	v_fma_f32 v95, v95, s12, -v45
	v_fma_f32 v96, v96, s12, -v46
	v_fma_f32 v97, v97, s12, -v47
	v_cndmask_b32_e64 v90, v191, v90, s[22:23]
	v_cndmask_b32_e64 v91, v191, v91, s[22:23]
	v_cndmask_b32_e64 v92, v191, v92, s[22:23]
	v_cndmask_b32_e64 v93, v191, v93, s[22:23]
	v_cndmask_b32_e64 v94, v191, v94, s[22:23]
	v_cndmask_b32_e64 v95, v191, v95, s[22:23]
	v_cndmask_b32_e64 v96, v191, v96, s[22:23]
	v_cndmask_b32_e64 v97, v191, v97, s[22:23]
	v_add_u32_e32 v60, 0xa600, v51
	ds_write_b32 v51, v90
	ds_write_b32 v51, v91 offset:10624
	ds_write_b32 v51, v92 offset:21248
	ds_write_b32 v51, v93 offset:31872
	ds_write_b32 v60, v94
	ds_write_b32 v60, v95 offset:10624
	ds_write_b32 v60, v96 offset:21248
	ds_write_b32 v60, v97 offset:31872
	v_fma_f32 v98, v98, s12, -v40
	v_fma_f32 v99, v99, s12, -v41
	v_fma_f32 v100, v100, s12, -v42
	v_fma_f32 v101, v101, s12, -v43
	v_fma_f32 v102, v102, s12, -v44
	v_fma_f32 v103, v103, s12, -v45
	v_fma_f32 v104, v104, s12, -v46
	v_fma_f32 v105, v105, s12, -v47
	v_cndmask_b32_e64 v98, v191, v98, s[24:25]
	v_cndmask_b32_e64 v99, v191, v99, s[24:25]
	v_cndmask_b32_e64 v100, v191, v100, s[24:25]
	v_cndmask_b32_e64 v101, v191, v101, s[24:25]
	v_cndmask_b32_e64 v102, v191, v102, s[24:25]
	v_cndmask_b32_e64 v103, v191, v103, s[24:25]
	v_cndmask_b32_e64 v104, v191, v104, s[24:25]
	v_cndmask_b32_e64 v105, v191, v105, s[24:25]
	v_add_u32_e32 v60, 0xa600, v52
	ds_write_b32 v52, v98
	ds_write_b32 v52, v99 offset:10624
	ds_write_b32 v52, v100 offset:21248
	ds_write_b32 v52, v101 offset:31872
	ds_write_b32 v60, v102
	ds_write_b32 v60, v103 offset:10624
	ds_write_b32 v60, v104 offset:21248
	ds_write_b32 v60, v105 offset:31872
	v_fma_f32 v106, v106, s12, -v40
	v_fma_f32 v107, v107, s12, -v41
	v_fma_f32 v108, v108, s12, -v42
	v_fma_f32 v109, v109, s12, -v43
	v_fma_f32 v110, v110, s12, -v44
	v_fma_f32 v111, v111, s12, -v45
	v_fma_f32 v112, v112, s12, -v46
	v_fma_f32 v113, v113, s12, -v47
	v_cndmask_b32_e64 v106, v191, v106, s[26:27]
	v_cndmask_b32_e64 v107, v191, v107, s[26:27]
	v_cndmask_b32_e64 v108, v191, v108, s[26:27]
	v_cndmask_b32_e64 v109, v191, v109, s[26:27]
	v_cndmask_b32_e64 v110, v191, v110, s[26:27]
	v_cndmask_b32_e64 v111, v191, v111, s[26:27]
	v_cndmask_b32_e64 v112, v191, v112, s[26:27]
	v_cndmask_b32_e64 v113, v191, v113, s[26:27]
	v_add_u32_e32 v60, 0xa600, v53
	s_mov_b64 exec, s[28:29]
	ds_write_b32 v53, v106
	ds_write_b32 v53, v107 offset:10624
	ds_write_b32 v53, v108 offset:21248
	ds_write_b32 v53, v109 offset:31872
	ds_write_b32 v60, v110
	ds_write_b32 v60, v111 offset:10624
	ds_write_b32 v60, v112 offset:21248
	ds_write_b32 v60, v113 offset:31872
	s_mov_b64 exec, -1
	s_branch .LBB0_259

.LBB0_358:
	s_or_b64 exec, exec, s[0:1]
	s_lshr_b32 s3, s2, 6
	s_and_b32 s0, s2, 63
	s_sub_i32 s12, 63, s0
	v_readlane_b32 s0, v253, 31
	v_and_b32_e32 v152, 31, v186
	v_bfe_u32 v153, v186, 5, 1
	s_lshl_b32 s1, s0, 2
	s_add_i32 s1, s1, s3
	s_lshl_b32 s1, s1, 18
	s_add_u32 s40, s16, s1
	s_addc_u32 s41, s17, 0
	s_add_u32 s42, s14, s1
	s_addc_u32 s43, s15, 0
	s_lshl_b32 s1, s0, 10
	s_lshl_b32 s4, s12, 5
	s_add_i32 s1, s1, s4
	v_add_u32_e32 v154, s1, v152
	v_lshlrev_b32_e32 v155, 10, v154
	v_lshl_add_u32 v155, v153, 4, v155
	s_lshl_b32 s1, s3, 7
	s_add_u32 s4, s10, s1
	s_addc_u32 s5, s11, 0
	global_load_dwordx4 v[48:51], v155, s[4:5]
	global_load_dwordx4 v[52:55], v155, s[4:5] offset:32
	global_load_dwordx4 v[56:59], v155, s[4:5] offset:64
	global_load_dwordx4 v[60:63], v155, s[4:5] offset:96
	v_and_b32_e32 v200, 63, v186
	v_lshlrev_b32_e32 v200, 4, v200
	v_lshlrev_b32_e32 v201, 5, v152
	v_lshl_add_u32 v201, v153, 4, v201
	s_lshl_b32 s1, s12, 12
	s_add_u32 s4, s40, s1
	s_addc_u32 s5, s41, 0
	global_load_dwordx4 v[66:69], v200, s[4:5]
	global_load_dwordx4 v[70:73], v200, s[4:5] offset:1024
	global_load_dwordx4 v[74:77], v200, s[4:5] offset:2048
	global_load_dwordx4 v[78:81], v200, s[4:5] offset:3072
	v_xor_b32_e32 v114, 32, v190
	v_lshlrev_b32_e32 v114, 2, v114
	v_lshlrev_b32_e32 v115, 2, v153
	v_sub_u32_e32 v115, v152, v115
	v_sub_u32_e32 v116, 1, v153
	v_sub_u32_e32 v116, 0, v116
	v_lshlrev_b32_e32 v156, 13, v154
	v_lshl_add_u32 v156, v153, 4, v156
	s_lshl_b32 s1, s3, 8
	s_add_i32 s1, s1, 0x1800
	v_add_u32_e32 v156, s1, v156
	s_add_u32 s4, s54, 0x20000000
	s_addc_u32 s5, s55, 0
	v_mov_b32_e32 v161, s5
	v_add_co_u32_e32 v160, vcc, s4, v156
	s_nop 1
	v_addc_co_u32_e32 v161, vcc, 0, v161, vcc
	v_mov_b32_e32 v127, 0
	v_mov_b32_e32 v0, 0
	v_mov_b32_e32 v1, 0
	v_mov_b32_e32 v2, 0
	v_mov_b32_e32 v3, 0
	v_mov_b32_e32 v4, 0
	v_mov_b32_e32 v5, 0
	v_mov_b32_e32 v6, 0
	v_mov_b32_e32 v7, 0
	v_mov_b32_e32 v8, 0
	v_mov_b32_e32 v9, 0
	v_mov_b32_e32 v10, 0
	v_mov_b32_e32 v11, 0
	v_mov_b32_e32 v12, 0
	v_mov_b32_e32 v13, 0
	v_mov_b32_e32 v14, 0
	v_mov_b32_e32 v15, 0
	v_mov_b32_e32 v16, 0
	v_mov_b32_e32 v17, 0
	v_mov_b32_e32 v18, 0
	v_mov_b32_e32 v19, 0
	v_mov_b32_e32 v20, 0
	v_mov_b32_e32 v21, 0
	v_mov_b32_e32 v22, 0
	v_mov_b32_e32 v23, 0
	v_mov_b32_e32 v24, 0
	v_mov_b32_e32 v25, 0
	v_mov_b32_e32 v26, 0
	v_mov_b32_e32 v27, 0
	v_mov_b32_e32 v28, 0
	v_mov_b32_e32 v29, 0
	v_mov_b32_e32 v30, 0
	v_mov_b32_e32 v31, 0
	s_sub_i32 s0, s12, 1
	s_max_i32 s0, s0, 0
	s_lshl_b32 s0, s0, 12
	s_add_u32 s2, s40, s0
	s_addc_u32 s3, s41, 0
	s_lshl_b32 s0, s12, 12
	s_add_u32 s18, s42, s0
	s_addc_u32 s19, s43, 0
	s_waitcnt vmcnt(0)
	global_load_dwordx4 v[82:85], v200, s[2:3]
	global_load_dwordx4 v[86:89], v200, s[2:3] offset:1024
	global_load_dwordx4 v[90:93], v200, s[2:3] offset:2048
	global_load_dwordx4 v[94:97], v200, s[2:3] offset:3072
	global_load_dwordx4 v[98:101], v201, s[18:19]
	global_load_dwordx4 v[102:105], v201, s[18:19] offset:1024
	global_load_dwordx4 v[106:109], v201, s[18:19] offset:2048
	global_load_dwordx4 v[110:113], v201, s[18:19] offset:3072
	v_mfma_f32_32x32x16_bf16 v[32:47], v[66:69], v[48:51], 0
	v_mfma_f32_32x32x16_bf16 v[32:47], v[70:73], v[52:55], v[32:47]
	v_mfma_f32_32x32x16_bf16 v[32:47], v[74:77], v[56:59], v[32:47]
	v_mfma_f32_32x32x16_bf16 v[32:47], v[78:81], v[60:63], v[32:47]
	s_nop 11
	v_mul_f32_e32 v44, 0x3fb8aa3b, v44
	v_mul_f32_e32 v45, 0x3fb8aa3b, v45
	v_mul_f32_e32 v46, 0x3fb8aa3b, v46
	v_mul_f32_e32 v47, 0x3fb8aa3b, v47
	v_exp_f32_e64 v152, -|v44|
	v_exp_f32_e64 v153, -|v45|
	v_exp_f32_e64 v154, -|v46|
	v_exp_f32_e64 v155, -|v47|
	v_max_f32_e32 v140, 0, v44
	v_max_f32_e32 v141, 0, v45
	v_max_f32_e32 v142, 0, v46
	v_max_f32_e32 v143, 0, v47
	v_add_f32_e32 v152, 1.0, v152
	v_add_f32_e32 v153, 1.0, v153
	v_add_f32_e32 v154, 1.0, v154
	v_add_f32_e32 v155, 1.0, v155
	v_log_f32_e32 v152, v152
	v_log_f32_e32 v153, v153
	v_log_f32_e32 v154, v154
	v_log_f32_e32 v155, v155
	s_nop 0
	v_add_f32_e32 v140, v140, v152
	v_add_f32_e32 v141, v141, v153
	v_add_f32_e32 v142, v142, v154
	v_add_f32_e32 v143, v143, v155
	v_cmp_lt_i32_e64 s[0:1], 24, v115
	v_cmp_lt_i32_e64 s[2:3], 25, v115
	v_cmp_lt_i32_e64 s[4:5], 26, v115
	v_cmp_lt_i32_e64 s[6:7], 27, v115
	s_nop 1
	v_cndmask_b32_e64 v140, 0, v140, s[0:1]
	v_cndmask_b32_e64 v141, 0, v141, s[2:3]
	v_cndmask_b32_e64 v142, 0, v142, s[4:5]
	v_cndmask_b32_e64 v143, 0, v143, s[6:7]
	v_add_f32_e32 v152, v140, v141
	v_add_f32_e32 v153, v142, v143
	v_add_f32_e32 v122, v152, v153
	ds_bpermute_b32 v126, v114, v122
	v_mul_f32_e32 v40, 0x3fb8aa3b, v40
	v_mul_f32_e32 v41, 0x3fb8aa3b, v41
	v_mul_f32_e32 v42, 0x3fb8aa3b, v42
	v_mul_f32_e32 v43, 0x3fb8aa3b, v43
	v_exp_f32_e64 v152, -|v40|
	v_exp_f32_e64 v153, -|v41|
	v_exp_f32_e64 v154, -|v42|
	v_exp_f32_e64 v155, -|v43|
	v_max_f32_e32 v136, 0, v40
	v_max_f32_e32 v137, 0, v41
	v_max_f32_e32 v138, 0, v42
	v_max_f32_e32 v139, 0, v43
	v_add_f32_e32 v152, 1.0, v152
	v_add_f32_e32 v153, 1.0, v153
	v_add_f32_e32 v154, 1.0, v154
	v_add_f32_e32 v155, 1.0, v155
	v_log_f32_e32 v152, v152
	v_log_f32_e32 v153, v153
	v_log_f32_e32 v154, v154
	v_log_f32_e32 v155, v155
	s_nop 0
	v_add_f32_e32 v136, v136, v152
	v_add_f32_e32 v137, v137, v153
	v_add_f32_e32 v138, v138, v154
	v_add_f32_e32 v139, v139, v155
	v_cmp_lt_i32_e64 s[0:1], 16, v115
	v_cmp_lt_i32_e64 s[2:3], 17, v115
	v_cmp_lt_i32_e64 s[4:5], 18, v115
	v_cmp_lt_i32_e64 s[6:7], 19, v115
	s_nop 1
	v_cndmask_b32_e64 v136, 0, v136, s[0:1]
	v_cndmask_b32_e64 v137, 0, v137, s[2:3]
	v_cndmask_b32_e64 v138, 0, v138, s[4:5]
	v_cndmask_b32_e64 v139, 0, v139, s[6:7]
	v_add_f32_e32 v152, v136, v137
	v_add_f32_e32 v153, v138, v139
	v_add_f32_e32 v121, v152, v153
	ds_bpermute_b32 v125, v114, v121
	v_mul_f32_e32 v36, 0x3fb8aa3b, v36
	v_mul_f32_e32 v37, 0x3fb8aa3b, v37
	v_mul_f32_e32 v38, 0x3fb8aa3b, v38
	v_mul_f32_e32 v39, 0x3fb8aa3b, v39
	v_exp_f32_e64 v152, -|v36|
	v_exp_f32_e64 v153, -|v37|
	v_exp_f32_e64 v154, -|v38|
	v_exp_f32_e64 v155, -|v39|
	v_max_f32_e32 v132, 0, v36
	v_max_f32_e32 v133, 0, v37
	v_max_f32_e32 v134, 0, v38
	v_max_f32_e32 v135, 0, v39
	v_add_f32_e32 v152, 1.0, v152
	v_add_f32_e32 v153, 1.0, v153
	v_add_f32_e32 v154, 1.0, v154
	v_add_f32_e32 v155, 1.0, v155
	v_log_f32_e32 v152, v152
	v_log_f32_e32 v153, v153
	v_log_f32_e32 v154, v154
	v_log_f32_e32 v155, v155
	s_nop 0
	v_add_f32_e32 v132, v132, v152
	v_add_f32_e32 v133, v133, v153
	v_add_f32_e32 v134, v134, v154
	v_add_f32_e32 v135, v135, v155
	v_cmp_lt_i32_e64 s[0:1], 8, v115
	v_cmp_lt_i32_e64 s[2:3], 9, v115
	v_cmp_lt_i32_e64 s[4:5], 10, v115
	v_cmp_lt_i32_e64 s[6:7], 11, v115
	s_nop 1
	v_cndmask_b32_e64 v132, 0, v132, s[0:1]
	v_cndmask_b32_e64 v133, 0, v133, s[2:3]
	v_cndmask_b32_e64 v134, 0, v134, s[4:5]
	v_cndmask_b32_e64 v135, 0, v135, s[6:7]
	v_add_f32_e32 v152, v132, v133
	v_add_f32_e32 v153, v134, v135
	v_add_f32_e32 v120, v152, v153
	ds_bpermute_b32 v124, v114, v120
	v_mul_f32_e32 v32, 0x3fb8aa3b, v32
	v_mul_f32_e32 v33, 0x3fb8aa3b, v33
	v_mul_f32_e32 v34, 0x3fb8aa3b, v34
	v_mul_f32_e32 v35, 0x3fb8aa3b, v35
	v_exp_f32_e64 v152, -|v32|
	v_exp_f32_e64 v153, -|v33|
	v_exp_f32_e64 v154, -|v34|
	v_exp_f32_e64 v155, -|v35|
	v_max_f32_e32 v128, 0, v32
	v_max_f32_e32 v129, 0, v33
	v_max_f32_e32 v130, 0, v34
	v_max_f32_e32 v131, 0, v35
	v_add_f32_e32 v152, 1.0, v152
	v_add_f32_e32 v153, 1.0, v153
	v_add_f32_e32 v154, 1.0, v154
	v_add_f32_e32 v155, 1.0, v155
	v_log_f32_e32 v152, v152
	v_log_f32_e32 v153, v153
	v_log_f32_e32 v154, v154
	v_log_f32_e32 v155, v155
	s_nop 0
	v_add_f32_e32 v128, v128, v152
	v_add_f32_e32 v129, v129, v153
	v_add_f32_e32 v130, v130, v154
	v_add_f32_e32 v131, v131, v155
	v_cmp_lt_i32_e64 s[0:1], 0, v115
	v_cmp_lt_i32_e64 s[2:3], 1, v115
	v_cmp_lt_i32_e64 s[4:5], 2, v115
	v_cmp_lt_i32_e64 s[6:7], 3, v115
	s_nop 1
	v_cndmask_b32_e64 v128, 0, v128, s[0:1]
	v_cndmask_b32_e64 v129, 0, v129, s[2:3]
	v_cndmask_b32_e64 v130, 0, v130, s[4:5]
	v_cndmask_b32_e64 v131, 0, v131, s[6:7]
	v_add_f32_e32 v152, v128, v129
	v_add_f32_e32 v153, v130, v131
	v_add_f32_e32 v119, v152, v153
	ds_bpermute_b32 v123, v114, v119
	s_waitcnt lgkmcnt(3)
	v_and_b32_e32 v152, v116, v126
	v_add_f32_e32 v153, v122, v126
	v_sub_f32_e32 v199, v127, v152
	v_sub_f32_e32 v127, v127, v153
	v_sub_f32_e32 v159, v199, v143
	v_sub_f32_e32 v158, v159, v142
	v_sub_f32_e32 v157, v158, v141
	v_sub_f32_e32 v156, v157, v140
	v_cmp_lt_i32_e64 s[0:1], 24, v115
	v_cmp_lt_i32_e64 s[2:3], 25, v115
	v_cmp_lt_i32_e64 s[4:5], 26, v115
	v_cmp_lt_i32_e64 s[6:7], 27, v115
	v_add_f32_e32 v44, v44, v156
	v_add_f32_e32 v45, v45, v157
	v_add_f32_e32 v46, v46, v158
	v_add_f32_e32 v47, v47, v159
	v_exp_f32_e32 v44, v44
	v_exp_f32_e32 v45, v45
	v_exp_f32_e32 v46, v46
	v_exp_f32_e32 v47, v47
	s_nop 0
	v_cndmask_b32_e64 v44, 0, v44, s[0:1]
	v_cndmask_b32_e64 v45, 0, v45, s[2:3]
	v_cndmask_b32_e64 v46, 0, v46, s[4:5]
	v_cndmask_b32_e64 v47, 0, v47, s[6:7]
	s_waitcnt lgkmcnt(2)
	v_and_b32_e32 v152, v116, v125
	v_add_f32_e32 v153, v121, v125
	v_sub_f32_e32 v199, v127, v152
	v_sub_f32_e32 v127, v127, v153
	v_sub_f32_e32 v159, v199, v139
	v_sub_f32_e32 v158, v159, v138
	v_sub_f32_e32 v157, v158, v137
	v_sub_f32_e32 v156, v157, v136
	v_cmp_lt_i32_e64 s[0:1], 16, v115
	v_cmp_lt_i32_e64 s[2:3], 17, v115
	v_cmp_lt_i32_e64 s[4:5], 18, v115
	v_cmp_lt_i32_e64 s[6:7], 19, v115
	v_add_f32_e32 v40, v40, v156
	v_add_f32_e32 v41, v41, v157
	v_add_f32_e32 v42, v42, v158
	v_add_f32_e32 v43, v43, v159
	v_exp_f32_e32 v40, v40
	v_exp_f32_e32 v41, v41
	v_exp_f32_e32 v42, v42
	v_exp_f32_e32 v43, v43
	s_nop 0
	v_cndmask_b32_e64 v40, 0, v40, s[0:1]
	v_cndmask_b32_e64 v41, 0, v41, s[2:3]
	v_cndmask_b32_e64 v42, 0, v42, s[4:5]
	v_cndmask_b32_e64 v43, 0, v43, s[6:7]
	s_waitcnt lgkmcnt(1)
	v_and_b32_e32 v152, v116, v124
	v_add_f32_e32 v153, v120, v124
	v_sub_f32_e32 v199, v127, v152
	v_sub_f32_e32 v127, v127, v153
	v_sub_f32_e32 v159, v199, v135
	v_sub_f32_e32 v158, v159, v134
	v_sub_f32_e32 v157, v158, v133
	v_sub_f32_e32 v156, v157, v132
	v_cmp_lt_i32_e64 s[0:1], 8, v115
	v_cmp_lt_i32_e64 s[2:3], 9, v115
	v_cmp_lt_i32_e64 s[4:5], 10, v115
	v_cmp_lt_i32_e64 s[6:7], 11, v115
	v_add_f32_e32 v36, v36, v156
	v_add_f32_e32 v37, v37, v157
	v_add_f32_e32 v38, v38, v158
	v_add_f32_e32 v39, v39, v159
	v_exp_f32_e32 v36, v36
	v_exp_f32_e32 v37, v37
	v_exp_f32_e32 v38, v38
	v_exp_f32_e32 v39, v39
	s_nop 0
	v_cndmask_b32_e64 v36, 0, v36, s[0:1]
	v_cndmask_b32_e64 v37, 0, v37, s[2:3]
	v_cndmask_b32_e64 v38, 0, v38, s[4:5]
	v_cndmask_b32_e64 v39, 0, v39, s[6:7]
	s_waitcnt lgkmcnt(0)
	v_and_b32_e32 v152, v116, v123
	v_add_f32_e32 v153, v119, v123
	v_sub_f32_e32 v199, v127, v152
	v_sub_f32_e32 v127, v127, v153
	v_sub_f32_e32 v159, v199, v131
	v_sub_f32_e32 v158, v159, v130
	v_sub_f32_e32 v157, v158, v129
	v_sub_f32_e32 v156, v157, v128
	v_cmp_lt_i32_e64 s[0:1], 0, v115
	v_cmp_lt_i32_e64 s[2:3], 1, v115
	v_cmp_lt_i32_e64 s[4:5], 2, v115
	v_cmp_lt_i32_e64 s[6:7], 3, v115
	v_add_f32_e32 v32, v32, v156
	v_add_f32_e32 v33, v33, v157
	v_add_f32_e32 v34, v34, v158
	v_add_f32_e32 v35, v35, v159
	v_exp_f32_e32 v32, v32
	v_exp_f32_e32 v33, v33
	v_exp_f32_e32 v34, v34
	v_exp_f32_e32 v35, v35
	s_nop 0
	v_cndmask_b32_e64 v32, 0, v32, s[0:1]
	v_cndmask_b32_e64 v33, 0, v33, s[2:3]
	v_cndmask_b32_e64 v34, 0, v34, s[4:5]
	v_cndmask_b32_e64 v35, 0, v35, s[6:7]
	v_cvt_pk_bf16_f32 v144, v32, v33
	v_cvt_pk_bf16_f32 v145, v34, v35
	v_cvt_pk_bf16_f32 v146, v36, v37
	v_cvt_pk_bf16_f32 v147, v38, v39
	v_cvt_pk_bf16_f32 v148, v40, v41
	v_cvt_pk_bf16_f32 v149, v42, v43
	v_cvt_pk_bf16_f32 v150, v44, v45
	v_cvt_pk_bf16_f32 v151, v46, v47
	v_cmp_gt_f32_e32 vcc, 0xc3177ba5, v127
	s_waitcnt vmcnt(0)
	v_mfma_f32_32x32x16_bf16 v[16:31], v[98:101], v[144:147], v[16:31]
	v_mfma_f32_32x32x16_bf16 v[0:15], v[102:105], v[144:147], v[0:15]
	v_mfma_f32_32x32x16_bf16 v[16:31], v[106:109], v[148:151], v[16:31]
	v_mfma_f32_32x32x16_bf16 v[0:15], v[110:113], v[148:151], v[0:15]
	s_cmp_eq_u64 vcc, exec
	s_cselect_b32 s0, 1, 0
	s_cmp_eq_u32 s12, 0
	s_cselect_b32 s1, 1, 0
	s_or_b32 s0, s0, s1
	s_sub_i32 s12, s12, 1
	s_cmp_lg_u32 s0, 0
	s_cbranch_scc1 .Lsb_done
.Lsb_loop:
	s_sub_i32 s0, s12, 1
	s_max_i32 s0, s0, 0
	s_lshl_b32 s0, s0, 12
	s_add_u32 s2, s40, s0
	s_addc_u32 s3, s41, 0
	s_lshl_b32 s0, s12, 12
	s_add_u32 s18, s42, s0
	s_addc_u32 s19, s43, 0
	s_waitcnt vmcnt(0)
	global_load_dwordx4 v[66:69], v200, s[2:3]
	global_load_dwordx4 v[70:73], v200, s[2:3] offset:1024
	global_load_dwordx4 v[74:77], v200, s[2:3] offset:2048
	global_load_dwordx4 v[78:81], v200, s[2:3] offset:3072
	global_load_dwordx4 v[98:101], v201, s[18:19]
	global_load_dwordx4 v[102:105], v201, s[18:19] offset:1024
	global_load_dwordx4 v[106:109], v201, s[18:19] offset:2048
	global_load_dwordx4 v[110:113], v201, s[18:19] offset:3072
	v_mfma_f32_32x32x16_bf16 v[32:47], v[82:85], v[48:51], 0
	v_mfma_f32_32x32x16_bf16 v[32:47], v[86:89], v[52:55], v[32:47]
	v_mfma_f32_32x32x16_bf16 v[32:47], v[90:93], v[56:59], v[32:47]
	v_mfma_f32_32x32x16_bf16 v[32:47], v[94:97], v[60:63], v[32:47]
	s_nop 11
	v_mul_f32_e32 v44, 0x3fb8aa3b, v44
	v_mul_f32_e32 v45, 0x3fb8aa3b, v45
	v_mul_f32_e32 v46, 0x3fb8aa3b, v46
	v_mul_f32_e32 v47, 0x3fb8aa3b, v47
	v_exp_f32_e64 v152, -|v44|
	v_exp_f32_e64 v153, -|v45|
	v_exp_f32_e64 v154, -|v46|
	v_exp_f32_e64 v155, -|v47|
	v_max_f32_e32 v140, 0, v44
	v_max_f32_e32 v141, 0, v45
	v_max_f32_e32 v142, 0, v46
	v_max_f32_e32 v143, 0, v47
	v_add_f32_e32 v152, 1.0, v152
	v_add_f32_e32 v153, 1.0, v153
	v_add_f32_e32 v154, 1.0, v154
	v_add_f32_e32 v155, 1.0, v155
	v_log_f32_e32 v152, v152
	v_log_f32_e32 v153, v153
	v_log_f32_e32 v154, v154
	v_log_f32_e32 v155, v155
	s_nop 0
	v_add_f32_e32 v140, v140, v152
	v_add_f32_e32 v141, v141, v153
	v_add_f32_e32 v142, v142, v154
	v_add_f32_e32 v143, v143, v155
	v_add_f32_e32 v152, v140, v141
	v_add_f32_e32 v153, v142, v143
	v_add_f32_e32 v122, v152, v153
	ds_bpermute_b32 v126, v114, v122
	v_mul_f32_e32 v40, 0x3fb8aa3b, v40
	v_mul_f32_e32 v41, 0x3fb8aa3b, v41
	v_mul_f32_e32 v42, 0x3fb8aa3b, v42
	v_mul_f32_e32 v43, 0x3fb8aa3b, v43
	v_exp_f32_e64 v152, -|v40|
	v_exp_f32_e64 v153, -|v41|
	v_exp_f32_e64 v154, -|v42|
	v_exp_f32_e64 v155, -|v43|
	v_max_f32_e32 v136, 0, v40
	v_max_f32_e32 v137, 0, v41
	v_max_f32_e32 v138, 0, v42
	v_max_f32_e32 v139, 0, v43
	v_add_f32_e32 v152, 1.0, v152
	v_add_f32_e32 v153, 1.0, v153
	v_add_f32_e32 v154, 1.0, v154
	v_add_f32_e32 v155, 1.0, v155
	v_log_f32_e32 v152, v152
	v_log_f32_e32 v153, v153
	v_log_f32_e32 v154, v154
	v_log_f32_e32 v155, v155
	s_nop 0
	v_add_f32_e32 v136, v136, v152
	v_add_f32_e32 v137, v137, v153
	v_add_f32_e32 v138, v138, v154
	v_add_f32_e32 v139, v139, v155
	v_add_f32_e32 v152, v136, v137
	v_add_f32_e32 v153, v138, v139
	v_add_f32_e32 v121, v152, v153
	ds_bpermute_b32 v125, v114, v121
	v_mul_f32_e32 v36, 0x3fb8aa3b, v36
	v_mul_f32_e32 v37, 0x3fb8aa3b, v37
	v_mul_f32_e32 v38, 0x3fb8aa3b, v38
	v_mul_f32_e32 v39, 0x3fb8aa3b, v39
	v_exp_f32_e64 v152, -|v36|
	v_exp_f32_e64 v153, -|v37|
	v_exp_f32_e64 v154, -|v38|
	v_exp_f32_e64 v155, -|v39|
	v_max_f32_e32 v132, 0, v36
	v_max_f32_e32 v133, 0, v37
	v_max_f32_e32 v134, 0, v38
	v_max_f32_e32 v135, 0, v39
	v_add_f32_e32 v152, 1.0, v152
	v_add_f32_e32 v153, 1.0, v153
	v_add_f32_e32 v154, 1.0, v154
	v_add_f32_e32 v155, 1.0, v155
	v_log_f32_e32 v152, v152
	v_log_f32_e32 v153, v153
	v_log_f32_e32 v154, v154
	v_log_f32_e32 v155, v155
	s_nop 0
	v_add_f32_e32 v132, v132, v152
	v_add_f32_e32 v133, v133, v153
	v_add_f32_e32 v134, v134, v154
	v_add_f32_e32 v135, v135, v155
	v_add_f32_e32 v152, v132, v133
	v_add_f32_e32 v153, v134, v135
	v_add_f32_e32 v120, v152, v153
	ds_bpermute_b32 v124, v114, v120
	v_mul_f32_e32 v32, 0x3fb8aa3b, v32
	v_mul_f32_e32 v33, 0x3fb8aa3b, v33
	v_mul_f32_e32 v34, 0x3fb8aa3b, v34
	v_mul_f32_e32 v35, 0x3fb8aa3b, v35
	v_exp_f32_e64 v152, -|v32|
	v_exp_f32_e64 v153, -|v33|
	v_exp_f32_e64 v154, -|v34|
	v_exp_f32_e64 v155, -|v35|
	v_max_f32_e32 v128, 0, v32
	v_max_f32_e32 v129, 0, v33
	v_max_f32_e32 v130, 0, v34
	v_max_f32_e32 v131, 0, v35
	v_add_f32_e32 v152, 1.0, v152
	v_add_f32_e32 v153, 1.0, v153
	v_add_f32_e32 v154, 1.0, v154
	v_add_f32_e32 v155, 1.0, v155
	v_log_f32_e32 v152, v152
	v_log_f32_e32 v153, v153
	v_log_f32_e32 v154, v154
	v_log_f32_e32 v155, v155
	s_nop 0
	v_add_f32_e32 v128, v128, v152
	v_add_f32_e32 v129, v129, v153
	v_add_f32_e32 v130, v130, v154
	v_add_f32_e32 v131, v131, v155
	v_add_f32_e32 v152, v128, v129
	v_add_f32_e32 v153, v130, v131
	v_add_f32_e32 v119, v152, v153
	ds_bpermute_b32 v123, v114, v119
	s_waitcnt lgkmcnt(3)
	v_and_b32_e32 v152, v116, v126
	v_add_f32_e32 v153, v122, v126
	v_sub_f32_e32 v199, v127, v152
	v_sub_f32_e32 v127, v127, v153
	v_sub_f32_e32 v159, v199, v143
	v_sub_f32_e32 v158, v159, v142
	v_sub_f32_e32 v157, v158, v141
	v_sub_f32_e32 v156, v157, v140
	v_add_f32_e32 v44, v44, v156
	v_add_f32_e32 v45, v45, v157
	v_add_f32_e32 v46, v46, v158
	v_add_f32_e32 v47, v47, v159
	v_exp_f32_e32 v44, v44
	v_exp_f32_e32 v45, v45
	v_exp_f32_e32 v46, v46
	v_exp_f32_e32 v47, v47
	s_waitcnt lgkmcnt(2)
	v_and_b32_e32 v152, v116, v125
	v_add_f32_e32 v153, v121, v125
	v_sub_f32_e32 v199, v127, v152
	v_sub_f32_e32 v127, v127, v153
	v_sub_f32_e32 v159, v199, v139
	v_sub_f32_e32 v158, v159, v138
	v_sub_f32_e32 v157, v158, v137
	v_sub_f32_e32 v156, v157, v136
	v_add_f32_e32 v40, v40, v156
	v_add_f32_e32 v41, v41, v157
	v_add_f32_e32 v42, v42, v158
	v_add_f32_e32 v43, v43, v159
	v_exp_f32_e32 v40, v40
	v_exp_f32_e32 v41, v41
	v_exp_f32_e32 v42, v42
	v_exp_f32_e32 v43, v43
	s_waitcnt lgkmcnt(1)
	v_and_b32_e32 v152, v116, v124
	v_add_f32_e32 v153, v120, v124
	v_sub_f32_e32 v199, v127, v152
	v_sub_f32_e32 v127, v127, v153
	v_sub_f32_e32 v159, v199, v135
	v_sub_f32_e32 v158, v159, v134
	v_sub_f32_e32 v157, v158, v133
	v_sub_f32_e32 v156, v157, v132
	v_add_f32_e32 v36, v36, v156
	v_add_f32_e32 v37, v37, v157
	v_add_f32_e32 v38, v38, v158
	v_add_f32_e32 v39, v39, v159
	v_exp_f32_e32 v36, v36
	v_exp_f32_e32 v37, v37
	v_exp_f32_e32 v38, v38
	v_exp_f32_e32 v39, v39
	s_waitcnt lgkmcnt(0)
	v_and_b32_e32 v152, v116, v123
	v_add_f32_e32 v153, v119, v123
	v_sub_f32_e32 v199, v127, v152
	v_sub_f32_e32 v127, v127, v153
	v_sub_f32_e32 v159, v199, v131
	v_sub_f32_e32 v158, v159, v130
	v_sub_f32_e32 v157, v158, v129
	v_sub_f32_e32 v156, v157, v128
	v_add_f32_e32 v32, v32, v156
	v_add_f32_e32 v33, v33, v157
	v_add_f32_e32 v34, v34, v158
	v_add_f32_e32 v35, v35, v159
	v_exp_f32_e32 v32, v32
	v_exp_f32_e32 v33, v33
	v_exp_f32_e32 v34, v34
	v_exp_f32_e32 v35, v35
	v_cvt_pk_bf16_f32 v144, v32, v33
	v_cvt_pk_bf16_f32 v145, v34, v35
	v_cvt_pk_bf16_f32 v146, v36, v37
	v_cvt_pk_bf16_f32 v147, v38, v39
	v_cvt_pk_bf16_f32 v148, v40, v41
	v_cvt_pk_bf16_f32 v149, v42, v43
	v_cvt_pk_bf16_f32 v150, v44, v45
	v_cvt_pk_bf16_f32 v151, v46, v47
	v_cmp_gt_f32_e32 vcc, 0xc3177ba5, v127
	s_waitcnt vmcnt(0)
	v_mfma_f32_32x32x16_bf16 v[16:31], v[98:101], v[144:147], v[16:31]
	v_mfma_f32_32x32x16_bf16 v[0:15], v[102:105], v[144:147], v[0:15]
	v_mfma_f32_32x32x16_bf16 v[16:31], v[106:109], v[148:151], v[16:31]
	v_mfma_f32_32x32x16_bf16 v[0:15], v[110:113], v[148:151], v[0:15]
	s_cmp_eq_u64 vcc, exec
	s_cselect_b32 s0, 1, 0
	s_cmp_eq_u32 s12, 0
	s_cselect_b32 s1, 1, 0
	s_or_b32 s0, s0, s1
	s_sub_i32 s12, s12, 1
	s_cmp_lg_u32 s0, 0
	s_cbranch_scc1 .Lsb_done
	s_sub_i32 s0, s12, 1
	s_max_i32 s0, s0, 0
	s_lshl_b32 s0, s0, 12
	s_add_u32 s2, s40, s0
	s_addc_u32 s3, s41, 0
	s_lshl_b32 s0, s12, 12
	s_add_u32 s18, s42, s0
	s_addc_u32 s19, s43, 0
	s_waitcnt vmcnt(0)
	global_load_dwordx4 v[82:85], v200, s[2:3]
	global_load_dwordx4 v[86:89], v200, s[2:3] offset:1024
	global_load_dwordx4 v[90:93], v200, s[2:3] offset:2048
	global_load_dwordx4 v[94:97], v200, s[2:3] offset:3072
	global_load_dwordx4 v[98:101], v201, s[18:19]
	global_load_dwordx4 v[102:105], v201, s[18:19] offset:1024
	global_load_dwordx4 v[106:109], v201, s[18:19] offset:2048
	global_load_dwordx4 v[110:113], v201, s[18:19] offset:3072
	v_mfma_f32_32x32x16_bf16 v[32:47], v[66:69], v[48:51], 0
	v_mfma_f32_32x32x16_bf16 v[32:47], v[70:73], v[52:55], v[32:47]
	v_mfma_f32_32x32x16_bf16 v[32:47], v[74:77], v[56:59], v[32:47]
	v_mfma_f32_32x32x16_bf16 v[32:47], v[78:81], v[60:63], v[32:47]
	s_nop 11
	v_mul_f32_e32 v44, 0x3fb8aa3b, v44
	v_mul_f32_e32 v45, 0x3fb8aa3b, v45
	v_mul_f32_e32 v46, 0x3fb8aa3b, v46
	v_mul_f32_e32 v47, 0x3fb8aa3b, v47
	v_exp_f32_e64 v152, -|v44|
	v_exp_f32_e64 v153, -|v45|
	v_exp_f32_e64 v154, -|v46|
	v_exp_f32_e64 v155, -|v47|
	v_max_f32_e32 v140, 0, v44
	v_max_f32_e32 v141, 0, v45
	v_max_f32_e32 v142, 0, v46
	v_max_f32_e32 v143, 0, v47
	v_add_f32_e32 v152, 1.0, v152
	v_add_f32_e32 v153, 1.0, v153
	v_add_f32_e32 v154, 1.0, v154
	v_add_f32_e32 v155, 1.0, v155
	v_log_f32_e32 v152, v152
	v_log_f32_e32 v153, v153
	v_log_f32_e32 v154, v154
	v_log_f32_e32 v155, v155
	s_nop 0
	v_add_f32_e32 v140, v140, v152
	v_add_f32_e32 v141, v141, v153
	v_add_f32_e32 v142, v142, v154
	v_add_f32_e32 v143, v143, v155
	v_add_f32_e32 v152, v140, v141
	v_add_f32_e32 v153, v142, v143
	v_add_f32_e32 v122, v152, v153
	ds_bpermute_b32 v126, v114, v122
	v_mul_f32_e32 v40, 0x3fb8aa3b, v40
	v_mul_f32_e32 v41, 0x3fb8aa3b, v41
	v_mul_f32_e32 v42, 0x3fb8aa3b, v42
	v_mul_f32_e32 v43, 0x3fb8aa3b, v43
	v_exp_f32_e64 v152, -|v40|
	v_exp_f32_e64 v153, -|v41|
	v_exp_f32_e64 v154, -|v42|
	v_exp_f32_e64 v155, -|v43|
	v_max_f32_e32 v136, 0, v40
	v_max_f32_e32 v137, 0, v41
	v_max_f32_e32 v138, 0, v42
	v_max_f32_e32 v139, 0, v43
	v_add_f32_e32 v152, 1.0, v152
	v_add_f32_e32 v153, 1.0, v153
	v_add_f32_e32 v154, 1.0, v154
	v_add_f32_e32 v155, 1.0, v155
	v_log_f32_e32 v152, v152
	v_log_f32_e32 v153, v153
	v_log_f32_e32 v154, v154
	v_log_f32_e32 v155, v155
	s_nop 0
	v_add_f32_e32 v136, v136, v152
	v_add_f32_e32 v137, v137, v153
	v_add_f32_e32 v138, v138, v154
	v_add_f32_e32 v139, v139, v155
	v_add_f32_e32 v152, v136, v137
	v_add_f32_e32 v153, v138, v139
	v_add_f32_e32 v121, v152, v153
	ds_bpermute_b32 v125, v114, v121
	v_mul_f32_e32 v36, 0x3fb8aa3b, v36
	v_mul_f32_e32 v37, 0x3fb8aa3b, v37
	v_mul_f32_e32 v38, 0x3fb8aa3b, v38
	v_mul_f32_e32 v39, 0x3fb8aa3b, v39
	v_exp_f32_e64 v152, -|v36|
	v_exp_f32_e64 v153, -|v37|
	v_exp_f32_e64 v154, -|v38|
	v_exp_f32_e64 v155, -|v39|
	v_max_f32_e32 v132, 0, v36
	v_max_f32_e32 v133, 0, v37
	v_max_f32_e32 v134, 0, v38
	v_max_f32_e32 v135, 0, v39
	v_add_f32_e32 v152, 1.0, v152
	v_add_f32_e32 v153, 1.0, v153
	v_add_f32_e32 v154, 1.0, v154
	v_add_f32_e32 v155, 1.0, v155
	v_log_f32_e32 v152, v152
	v_log_f32_e32 v153, v153
	v_log_f32_e32 v154, v154
	v_log_f32_e32 v155, v155
	s_nop 0
	v_add_f32_e32 v132, v132, v152
	v_add_f32_e32 v133, v133, v153
	v_add_f32_e32 v134, v134, v154
	v_add_f32_e32 v135, v135, v155
	v_add_f32_e32 v152, v132, v133
	v_add_f32_e32 v153, v134, v135
	v_add_f32_e32 v120, v152, v153
	ds_bpermute_b32 v124, v114, v120
	v_mul_f32_e32 v32, 0x3fb8aa3b, v32
	v_mul_f32_e32 v33, 0x3fb8aa3b, v33
	v_mul_f32_e32 v34, 0x3fb8aa3b, v34
	v_mul_f32_e32 v35, 0x3fb8aa3b, v35
	v_exp_f32_e64 v152, -|v32|
	v_exp_f32_e64 v153, -|v33|
	v_exp_f32_e64 v154, -|v34|
	v_exp_f32_e64 v155, -|v35|
	v_max_f32_e32 v128, 0, v32
	v_max_f32_e32 v129, 0, v33
	v_max_f32_e32 v130, 0, v34
	v_max_f32_e32 v131, 0, v35
	v_add_f32_e32 v152, 1.0, v152
	v_add_f32_e32 v153, 1.0, v153
	v_add_f32_e32 v154, 1.0, v154
	v_add_f32_e32 v155, 1.0, v155
	v_log_f32_e32 v152, v152
	v_log_f32_e32 v153, v153
	v_log_f32_e32 v154, v154
	v_log_f32_e32 v155, v155
	s_nop 0
	v_add_f32_e32 v128, v128, v152
	v_add_f32_e32 v129, v129, v153
	v_add_f32_e32 v130, v130, v154
	v_add_f32_e32 v131, v131, v155
	v_add_f32_e32 v152, v128, v129
	v_add_f32_e32 v153, v130, v131
	v_add_f32_e32 v119, v152, v153
	ds_bpermute_b32 v123, v114, v119
	s_waitcnt lgkmcnt(3)
	v_and_b32_e32 v152, v116, v126
	v_add_f32_e32 v153, v122, v126
	v_sub_f32_e32 v199, v127, v152
	v_sub_f32_e32 v127, v127, v153
	v_sub_f32_e32 v159, v199, v143
	v_sub_f32_e32 v158, v159, v142
	v_sub_f32_e32 v157, v158, v141
	v_sub_f32_e32 v156, v157, v140
	v_add_f32_e32 v44, v44, v156
	v_add_f32_e32 v45, v45, v157
	v_add_f32_e32 v46, v46, v158
	v_add_f32_e32 v47, v47, v159
	v_exp_f32_e32 v44, v44
	v_exp_f32_e32 v45, v45
	v_exp_f32_e32 v46, v46
	v_exp_f32_e32 v47, v47
	s_waitcnt lgkmcnt(2)
	v_and_b32_e32 v152, v116, v125
	v_add_f32_e32 v153, v121, v125
	v_sub_f32_e32 v199, v127, v152
	v_sub_f32_e32 v127, v127, v153
	v_sub_f32_e32 v159, v199, v139
	v_sub_f32_e32 v158, v159, v138
	v_sub_f32_e32 v157, v158, v137
	v_sub_f32_e32 v156, v157, v136
	v_add_f32_e32 v40, v40, v156
	v_add_f32_e32 v41, v41, v157
	v_add_f32_e32 v42, v42, v158
	v_add_f32_e32 v43, v43, v159
	v_exp_f32_e32 v40, v40
	v_exp_f32_e32 v41, v41
	v_exp_f32_e32 v42, v42
	v_exp_f32_e32 v43, v43
	s_waitcnt lgkmcnt(1)
	v_and_b32_e32 v152, v116, v124
	v_add_f32_e32 v153, v120, v124
	v_sub_f32_e32 v199, v127, v152
	v_sub_f32_e32 v127, v127, v153
	v_sub_f32_e32 v159, v199, v135
	v_sub_f32_e32 v158, v159, v134
	v_sub_f32_e32 v157, v158, v133
	v_sub_f32_e32 v156, v157, v132
	v_add_f32_e32 v36, v36, v156
	v_add_f32_e32 v37, v37, v157
	v_add_f32_e32 v38, v38, v158
	v_add_f32_e32 v39, v39, v159
	v_exp_f32_e32 v36, v36
	v_exp_f32_e32 v37, v37
	v_exp_f32_e32 v38, v38
	v_exp_f32_e32 v39, v39
	s_waitcnt lgkmcnt(0)
	v_and_b32_e32 v152, v116, v123
	v_add_f32_e32 v153, v119, v123
	v_sub_f32_e32 v199, v127, v152
	v_sub_f32_e32 v127, v127, v153
	v_sub_f32_e32 v159, v199, v131
	v_sub_f32_e32 v158, v159, v130
	v_sub_f32_e32 v157, v158, v129
	v_sub_f32_e32 v156, v157, v128
	v_add_f32_e32 v32, v32, v156
	v_add_f32_e32 v33, v33, v157
	v_add_f32_e32 v34, v34, v158
	v_add_f32_e32 v35, v35, v159
	v_exp_f32_e32 v32, v32
	v_exp_f32_e32 v33, v33
	v_exp_f32_e32 v34, v34
	v_exp_f32_e32 v35, v35
	v_cvt_pk_bf16_f32 v144, v32, v33
	v_cvt_pk_bf16_f32 v145, v34, v35
	v_cvt_pk_bf16_f32 v146, v36, v37
	v_cvt_pk_bf16_f32 v147, v38, v39
	v_cvt_pk_bf16_f32 v148, v40, v41
	v_cvt_pk_bf16_f32 v149, v42, v43
	v_cvt_pk_bf16_f32 v150, v44, v45
	v_cvt_pk_bf16_f32 v151, v46, v47
	v_cmp_gt_f32_e32 vcc, 0xc3177ba5, v127
	s_waitcnt vmcnt(0)
	v_mfma_f32_32x32x16_bf16 v[16:31], v[98:101], v[144:147], v[16:31]
	v_mfma_f32_32x32x16_bf16 v[0:15], v[102:105], v[144:147], v[0:15]
	v_mfma_f32_32x32x16_bf16 v[16:31], v[106:109], v[148:151], v[16:31]
	v_mfma_f32_32x32x16_bf16 v[0:15], v[110:113], v[148:151], v[0:15]
	s_cmp_eq_u64 vcc, exec
	s_cselect_b32 s0, 1, 0
	s_cmp_eq_u32 s12, 0
	s_cselect_b32 s1, 1, 0
	s_or_b32 s0, s0, s1
	s_sub_i32 s12, s12, 1
	s_cmp_lg_u32 s0, 0
	s_cbranch_scc0 .Lsb_loop

.LBB0_501:
	v_lshl_add_u32 v92, v45, 6, v46
	v_add_u32_e32 v93, v47, v45
	s_andn2_b64 s[38:39], exec, vcc
	v_add_u32_e32 v64, 0, v92
	v_lshlrev_b32_e32 v183, 2, v64
	v_lshlrev_b32_e32 v64, 8, v64
	v_lshl_add_u64 v[180:181], v[64:65], 0, v[36:37]
	v_mov_b32_e32 v96, 0
	v_mov_b32_e32 v97, 0
	v_mov_b32_e32 v98, 0
	v_mov_b32_e32 v99, 0
	v_add_u32_e32 v182, 0, v93
	v_cmp_gt_i32_e64 s[40:41], s80, v182
	v_add_u32_e32 v182, s44, v182
	v_mul_u32_u24_e32 v182, s66, v182
	v_add_u32_e32 v64, 0, v46
	v_lshl_add_u32 v182, v64, 1, v182
	s_and_b64 s[40:41], s[40:41], s[38:39]
	s_mov_b64 s[4:5], exec
	s_mov_b64 exec, s[40:41]
	global_load_dwordx4 v[96:99], v182, s[34:35]
	s_mov_b64 exec, s[0:1]
	global_load_dwordx4 v[100:103], v183, s[30:31]
	global_load_dwordx4 v[104:107], v183, s[30:31] offset:16
	s_mov_b64 exec, s[4:5]
	global_load_dword v108, v[180:181], off
	global_load_dword v109, v[180:181], off offset:256
	global_load_dword v110, v[180:181], off offset:512
	global_load_dword v111, v[180:181], off offset:768
	global_load_dword v112, v[180:181], off offset:1024
	global_load_dword v113, v[180:181], off offset:1280
	global_load_dword v114, v[180:181], off offset:1536
	global_load_dword v115, v[180:181], off offset:1792
	global_load_dword v116, v[180:181], off offset:128
	global_load_dword v117, v[180:181], off offset:384
	global_load_dword v118, v[180:181], off offset:640
	global_load_dword v119, v[180:181], off offset:896
	global_load_dword v120, v[180:181], off offset:1152
	global_load_dword v121, v[180:181], off offset:1408
	global_load_dword v122, v[180:181], off offset:1664
	global_load_dword v123, v[180:181], off offset:1920
	v_add_u32_e32 v64, 16, v92
	v_lshlrev_b32_e32 v183, 2, v64
	v_lshlrev_b32_e32 v64, 8, v64
	v_lshl_add_u64 v[180:181], v[64:65], 0, v[36:37]
	v_mov_b32_e32 v124, 0
	v_mov_b32_e32 v125, 0
	v_mov_b32_e32 v126, 0
	v_mov_b32_e32 v127, 0
	v_add_u32_e32 v182, 0, v93
	v_cmp_gt_i32_e64 s[40:41], s80, v182
	v_add_u32_e32 v182, s44, v182
	v_mul_u32_u24_e32 v182, s66, v182
	v_add_u32_e32 v64, 16, v46
	v_lshl_add_u32 v182, v64, 1, v182
	s_and_b64 s[40:41], s[40:41], s[38:39]
	s_mov_b64 s[4:5], exec
	s_mov_b64 exec, s[40:41]
	global_load_dwordx4 v[124:127], v182, s[34:35]
	s_mov_b64 exec, s[0:1]
	global_load_dwordx4 v[128:131], v183, s[30:31]
	global_load_dwordx4 v[132:135], v183, s[30:31] offset:16
	s_mov_b64 exec, s[4:5]
	global_load_dword v136, v[180:181], off
	global_load_dword v137, v[180:181], off offset:256
	global_load_dword v138, v[180:181], off offset:512
	global_load_dword v139, v[180:181], off offset:768
	global_load_dword v140, v[180:181], off offset:1024
	global_load_dword v141, v[180:181], off offset:1280
	global_load_dword v142, v[180:181], off offset:1536
	global_load_dword v143, v[180:181], off offset:1792
	global_load_dword v150, v[180:181], off offset:128
	global_load_dword v151, v[180:181], off offset:384
	global_load_dword v152, v[180:181], off offset:640
	global_load_dword v153, v[180:181], off offset:896
	global_load_dword v154, v[180:181], off offset:1152
	global_load_dword v155, v[180:181], off offset:1408
	global_load_dword v156, v[180:181], off offset:1664
	global_load_dword v157, v[180:181], off offset:1920
	s_waitcnt vmcnt(19)
	s_mov_b64 s[4:5], exec
	s_mov_b64 exec, s[0:1]
	v_cvt_pk_bf16_f32 v96, v100, v101
	v_cvt_pk_bf16_f32 v97, v102, v103
	v_cvt_pk_bf16_f32 v98, v104, v105
	v_cvt_pk_bf16_f32 v99, v106, v107
	s_mov_b64 exec, s[4:5]
	v_cvt_pk_bf16_f32 v158, v108, v109
	v_cvt_pk_bf16_f32 v159, v110, v111
	v_cvt_pk_bf16_f32 v160, v112, v113
	v_cvt_pk_bf16_f32 v161, v114, v115
	v_cvt_pk_bf16_f32 v176, v116, v117
	v_cvt_pk_bf16_f32 v177, v118, v119
	v_cvt_pk_bf16_f32 v178, v120, v121
	v_cvt_pk_bf16_f32 v179, v122, v123
	s_nop 1
	v_mfma_f32_32x32x16_bf16 v[16:31], v[96:99], v[158:161], v[16:31]
	v_mfma_f32_32x32x16_bf16 v[0:15], v[96:99], v[176:179], v[0:15]
	v_add_u32_e32 v64, 32, v92
	v_lshlrev_b32_e32 v183, 2, v64
	v_lshlrev_b32_e32 v64, 8, v64
	v_lshl_add_u64 v[180:181], v[64:65], 0, v[36:37]
	v_mov_b32_e32 v96, 0
	v_mov_b32_e32 v97, 0
	v_mov_b32_e32 v98, 0
	v_mov_b32_e32 v99, 0
	v_add_u32_e32 v182, 0, v93
	v_cmp_gt_i32_e64 s[40:41], s80, v182
	v_add_u32_e32 v182, s44, v182
	v_mul_u32_u24_e32 v182, s66, v182
	v_add_u32_e32 v64, 32, v46
	v_lshl_add_u32 v182, v64, 1, v182
	s_and_b64 s[40:41], s[40:41], s[38:39]
	s_mov_b64 s[4:5], exec
	s_mov_b64 exec, s[40:41]
	global_load_dwordx4 v[96:99], v182, s[34:35]
	s_mov_b64 exec, s[0:1]
	global_load_dwordx4 v[100:103], v183, s[30:31]
	global_load_dwordx4 v[104:107], v183, s[30:31] offset:16
	s_mov_b64 exec, s[4:5]
	global_load_dword v108, v[180:181], off
	global_load_dword v109, v[180:181], off offset:256
	global_load_dword v110, v[180:181], off offset:512
	global_load_dword v111, v[180:181], off offset:768
	global_load_dword v112, v[180:181], off offset:1024
	global_load_dword v113, v[180:181], off offset:1280
	global_load_dword v114, v[180:181], off offset:1536
	global_load_dword v115, v[180:181], off offset:1792
	global_load_dword v116, v[180:181], off offset:128
	global_load_dword v117, v[180:181], off offset:384
	global_load_dword v118, v[180:181], off offset:640
	global_load_dword v119, v[180:181], off offset:896
	global_load_dword v120, v[180:181], off offset:1152
	global_load_dword v121, v[180:181], off offset:1408
	global_load_dword v122, v[180:181], off offset:1664
	global_load_dword v123, v[180:181], off offset:1920
	s_waitcnt vmcnt(19)
	s_mov_b64 s[4:5], exec
	s_mov_b64 exec, s[0:1]
	v_cvt_pk_bf16_f32 v124, v128, v129
	v_cvt_pk_bf16_f32 v125, v130, v131
	v_cvt_pk_bf16_f32 v126, v132, v133
	v_cvt_pk_bf16_f32 v127, v134, v135
	s_mov_b64 exec, s[4:5]
	v_cvt_pk_bf16_f32 v158, v136, v137
	v_cvt_pk_bf16_f32 v159, v138, v139
	v_cvt_pk_bf16_f32 v160, v140, v141
	v_cvt_pk_bf16_f32 v161, v142, v143
	v_cvt_pk_bf16_f32 v176, v150, v151
	v_cvt_pk_bf16_f32 v177, v152, v153
	v_cvt_pk_bf16_f32 v178, v154, v155
	v_cvt_pk_bf16_f32 v179, v156, v157
	s_nop 1
	v_mfma_f32_32x32x16_bf16 v[16:31], v[124:127], v[158:161], v[16:31]
	v_mfma_f32_32x32x16_bf16 v[0:15], v[124:127], v[176:179], v[0:15]
	v_add_u32_e32 v64, 48, v92
	v_lshlrev_b32_e32 v183, 2, v64
	v_lshlrev_b32_e32 v64, 8, v64
	v_lshl_add_u64 v[180:181], v[64:65], 0, v[36:37]
	v_mov_b32_e32 v124, 0
	v_mov_b32_e32 v125, 0
	v_mov_b32_e32 v126, 0
	v_mov_b32_e32 v127, 0
	v_add_u32_e32 v182, 0, v93
	v_cmp_gt_i32_e64 s[40:41], s80, v182
	v_add_u32_e32 v182, s44, v182
	v_mul_u32_u24_e32 v182, s66, v182
	v_add_u32_e32 v64, 48, v46
	v_lshl_add_u32 v182, v64, 1, v182
	s_and_b64 s[40:41], s[40:41], s[38:39]
	s_mov_b64 s[4:5], exec
	s_mov_b64 exec, s[40:41]
	global_load_dwordx4 v[124:127], v182, s[34:35]
	s_mov_b64 exec, s[0:1]
	global_load_dwordx4 v[128:131], v183, s[30:31]
	global_load_dwordx4 v[132:135], v183, s[30:31] offset:16
	s_mov_b64 exec, s[4:5]
	global_load_dword v136, v[180:181], off
	global_load_dword v137, v[180:181], off offset:256
	global_load_dword v138, v[180:181], off offset:512
	global_load_dword v139, v[180:181], off offset:768
	global_load_dword v140, v[180:181], off offset:1024
	global_load_dword v141, v[180:181], off offset:1280
	global_load_dword v142, v[180:181], off offset:1536
	global_load_dword v143, v[180:181], off offset:1792
	global_load_dword v150, v[180:181], off offset:128
	global_load_dword v151, v[180:181], off offset:384
	global_load_dword v152, v[180:181], off offset:640
	global_load_dword v153, v[180:181], off offset:896
	global_load_dword v154, v[180:181], off offset:1152
	global_load_dword v155, v[180:181], off offset:1408
	global_load_dword v156, v[180:181], off offset:1664
	global_load_dword v157, v[180:181], off offset:1920
	s_waitcnt vmcnt(19)
	s_mov_b64 s[4:5], exec
	s_mov_b64 exec, s[0:1]
	v_cvt_pk_bf16_f32 v96, v100, v101
	v_cvt_pk_bf16_f32 v97, v102, v103
	v_cvt_pk_bf16_f32 v98, v104, v105
	v_cvt_pk_bf16_f32 v99, v106, v107
	s_mov_b64 exec, s[4:5]
	v_cvt_pk_bf16_f32 v158, v108, v109
	v_cvt_pk_bf16_f32 v159, v110, v111
	v_cvt_pk_bf16_f32 v160, v112, v113
	v_cvt_pk_bf16_f32 v161, v114, v115
	v_cvt_pk_bf16_f32 v176, v116, v117
	v_cvt_pk_bf16_f32 v177, v118, v119
	v_cvt_pk_bf16_f32 v178, v120, v121
	v_cvt_pk_bf16_f32 v179, v122, v123
	s_nop 1
	v_mfma_f32_32x32x16_bf16 v[16:31], v[96:99], v[158:161], v[16:31]
	v_mfma_f32_32x32x16_bf16 v[0:15], v[96:99], v[176:179], v[0:15]
	v_add_u32_e32 v64, 64, v92
	v_lshlrev_b32_e32 v183, 2, v64
	v_lshlrev_b32_e32 v64, 8, v64
	v_lshl_add_u64 v[180:181], v[64:65], 0, v[36:37]
	v_mov_b32_e32 v96, 0
	v_mov_b32_e32 v97, 0
	v_mov_b32_e32 v98, 0
	v_mov_b32_e32 v99, 0
	v_add_u32_e32 v182, 1, v93
	v_cmp_gt_i32_e64 s[40:41], s80, v182
	v_add_u32_e32 v182, s44, v182
	v_mul_u32_u24_e32 v182, s66, v182
	v_add_u32_e32 v64, 0, v46
	v_lshl_add_u32 v182, v64, 1, v182
	s_and_b64 s[40:41], s[40:41], s[38:39]
	s_mov_b64 s[4:5], exec
	s_mov_b64 exec, s[40:41]
	global_load_dwordx4 v[96:99], v182, s[34:35]
	s_mov_b64 exec, s[0:1]
	global_load_dwordx4 v[100:103], v183, s[30:31]
	global_load_dwordx4 v[104:107], v183, s[30:31] offset:16
	s_mov_b64 exec, s[4:5]
	global_load_dword v108, v[180:181], off
	global_load_dword v109, v[180:181], off offset:256
	global_load_dword v110, v[180:181], off offset:512
	global_load_dword v111, v[180:181], off offset:768
	global_load_dword v112, v[180:181], off offset:1024
	global_load_dword v113, v[180:181], off offset:1280
	global_load_dword v114, v[180:181], off offset:1536
	global_load_dword v115, v[180:181], off offset:1792
	global_load_dword v116, v[180:181], off offset:128
	global_load_dword v117, v[180:181], off offset:384
	global_load_dword v118, v[180:181], off offset:640
	global_load_dword v119, v[180:181], off offset:896
	global_load_dword v120, v[180:181], off offset:1152
	global_load_dword v121, v[180:181], off offset:1408
	global_load_dword v122, v[180:181], off offset:1664
	global_load_dword v123, v[180:181], off offset:1920
	s_waitcnt vmcnt(19)
	s_mov_b64 s[4:5], exec
	s_mov_b64 exec, s[0:1]
	v_cvt_pk_bf16_f32 v124, v128, v129
	v_cvt_pk_bf16_f32 v125, v130, v131
	v_cvt_pk_bf16_f32 v126, v132, v133
	v_cvt_pk_bf16_f32 v127, v134, v135
	s_mov_b64 exec, s[4:5]
	v_cvt_pk_bf16_f32 v158, v136, v137
	v_cvt_pk_bf16_f32 v159, v138, v139
	v_cvt_pk_bf16_f32 v160, v140, v141
	v_cvt_pk_bf16_f32 v161, v142, v143
	v_cvt_pk_bf16_f32 v176, v150, v151
	v_cvt_pk_bf16_f32 v177, v152, v153
	v_cvt_pk_bf16_f32 v178, v154, v155
	v_cvt_pk_bf16_f32 v179, v156, v157
	s_nop 1
	v_mfma_f32_32x32x16_bf16 v[16:31], v[124:127], v[158:161], v[16:31]
	v_mfma_f32_32x32x16_bf16 v[0:15], v[124:127], v[176:179], v[0:15]
	v_add_u32_e32 v64, 80, v92
	v_lshlrev_b32_e32 v183, 2, v64
	v_lshlrev_b32_e32 v64, 8, v64
	v_lshl_add_u64 v[180:181], v[64:65], 0, v[36:37]
	v_mov_b32_e32 v124, 0
	v_mov_b32_e32 v125, 0
	v_mov_b32_e32 v126, 0
	v_mov_b32_e32 v127, 0
	v_add_u32_e32 v182, 1, v93
	v_cmp_gt_i32_e64 s[40:41], s80, v182
	v_add_u32_e32 v182, s44, v182
	v_mul_u32_u24_e32 v182, s66, v182
	v_add_u32_e32 v64, 16, v46
	v_lshl_add_u32 v182, v64, 1, v182
	s_and_b64 s[40:41], s[40:41], s[38:39]
	s_mov_b64 s[4:5], exec
	s_mov_b64 exec, s[40:41]
	global_load_dwordx4 v[124:127], v182, s[34:35]
	s_mov_b64 exec, s[0:1]
	global_load_dwordx4 v[128:131], v183, s[30:31]
	global_load_dwordx4 v[132:135], v183, s[30:31] offset:16
	s_mov_b64 exec, s[4:5]
	global_load_dword v136, v[180:181], off
	global_load_dword v137, v[180:181], off offset:256
	global_load_dword v138, v[180:181], off offset:512
	global_load_dword v139, v[180:181], off offset:768
	global_load_dword v140, v[180:181], off offset:1024
	global_load_dword v141, v[180:181], off offset:1280
	global_load_dword v142, v[180:181], off offset:1536
	global_load_dword v143, v[180:181], off offset:1792
	global_load_dword v150, v[180:181], off offset:128
	global_load_dword v151, v[180:181], off offset:384
	global_load_dword v152, v[180:181], off offset:640
	global_load_dword v153, v[180:181], off offset:896
	global_load_dword v154, v[180:181], off offset:1152
	global_load_dword v155, v[180:181], off offset:1408
	global_load_dword v156, v[180:181], off offset:1664
	global_load_dword v157, v[180:181], off offset:1920
	s_waitcnt vmcnt(19)
	s_mov_b64 s[4:5], exec
	s_mov_b64 exec, s[0:1]
	v_cvt_pk_bf16_f32 v96, v100, v101
	v_cvt_pk_bf16_f32 v97, v102, v103
	v_cvt_pk_bf16_f32 v98, v104, v105
	v_cvt_pk_bf16_f32 v99, v106, v107
	s_mov_b64 exec, s[4:5]
	v_cvt_pk_bf16_f32 v158, v108, v109
	v_cvt_pk_bf16_f32 v159, v110, v111
	v_cvt_pk_bf16_f32 v160, v112, v113
	v_cvt_pk_bf16_f32 v161, v114, v115
	v_cvt_pk_bf16_f32 v176, v116, v117
	v_cvt_pk_bf16_f32 v177, v118, v119
	v_cvt_pk_bf16_f32 v178, v120, v121
	v_cvt_pk_bf16_f32 v179, v122, v123
	s_nop 1
	v_mfma_f32_32x32x16_bf16 v[16:31], v[96:99], v[158:161], v[16:31]
	v_mfma_f32_32x32x16_bf16 v[0:15], v[96:99], v[176:179], v[0:15]
	v_add_u32_e32 v64, 96, v92
	v_lshlrev_b32_e32 v183, 2, v64
	v_lshlrev_b32_e32 v64, 8, v64
	v_lshl_add_u64 v[180:181], v[64:65], 0, v[36:37]
	v_mov_b32_e32 v96, 0
	v_mov_b32_e32 v97, 0
	v_mov_b32_e32 v98, 0
	v_mov_b32_e32 v99, 0
	v_add_u32_e32 v182, 1, v93
	v_cmp_gt_i32_e64 s[40:41], s80, v182
	v_add_u32_e32 v182, s44, v182
	v_mul_u32_u24_e32 v182, s66, v182
	v_add_u32_e32 v64, 32, v46
	v_lshl_add_u32 v182, v64, 1, v182
	s_and_b64 s[40:41], s[40:41], s[38:39]
	s_mov_b64 s[4:5], exec
	s_mov_b64 exec, s[40:41]
	global_load_dwordx4 v[96:99], v182, s[34:35]
	s_mov_b64 exec, s[0:1]
	global_load_dwordx4 v[100:103], v183, s[30:31]
	global_load_dwordx4 v[104:107], v183, s[30:31] offset:16
	s_mov_b64 exec, s[4:5]
	global_load_dword v108, v[180:181], off
	global_load_dword v109, v[180:181], off offset:256
	global_load_dword v110, v[180:181], off offset:512
	global_load_dword v111, v[180:181], off offset:768
	global_load_dword v112, v[180:181], off offset:1024
	global_load_dword v113, v[180:181], off offset:1280
	global_load_dword v114, v[180:181], off offset:1536
	global_load_dword v115, v[180:181], off offset:1792
	global_load_dword v116, v[180:181], off offset:128
	global_load_dword v117, v[180:181], off offset:384
	global_load_dword v118, v[180:181], off offset:640
	global_load_dword v119, v[180:181], off offset:896
	global_load_dword v120, v[180:181], off offset:1152
	global_load_dword v121, v[180:181], off offset:1408
	global_load_dword v122, v[180:181], off offset:1664
	global_load_dword v123, v[180:181], off offset:1920
	s_waitcnt vmcnt(19)
	s_mov_b64 s[4:5], exec
	s_mov_b64 exec, s[0:1]
	v_cvt_pk_bf16_f32 v124, v128, v129
	v_cvt_pk_bf16_f32 v125, v130, v131
	v_cvt_pk_bf16_f32 v126, v132, v133
	v_cvt_pk_bf16_f32 v127, v134, v135
	s_mov_b64 exec, s[4:5]
	v_cvt_pk_bf16_f32 v158, v136, v137
	v_cvt_pk_bf16_f32 v159, v138, v139
	v_cvt_pk_bf16_f32 v160, v140, v141
	v_cvt_pk_bf16_f32 v161, v142, v143
	v_cvt_pk_bf16_f32 v176, v150, v151
	v_cvt_pk_bf16_f32 v177, v152, v153
	v_cvt_pk_bf16_f32 v178, v154, v155
	v_cvt_pk_bf16_f32 v179, v156, v157
	s_nop 1
	v_mfma_f32_32x32x16_bf16 v[16:31], v[124:127], v[158:161], v[16:31]
	v_mfma_f32_32x32x16_bf16 v[0:15], v[124:127], v[176:179], v[0:15]
	v_add_u32_e32 v64, 112, v92
	v_lshlrev_b32_e32 v183, 2, v64
	v_lshlrev_b32_e32 v64, 8, v64
	v_lshl_add_u64 v[180:181], v[64:65], 0, v[36:37]
	v_mov_b32_e32 v124, 0
	v_mov_b32_e32 v125, 0
	v_mov_b32_e32 v126, 0
	v_mov_b32_e32 v127, 0
	v_add_u32_e32 v182, 1, v93
	v_cmp_gt_i32_e64 s[40:41], s80, v182
	v_add_u32_e32 v182, s44, v182
	v_mul_u32_u24_e32 v182, s66, v182
	v_add_u32_e32 v64, 48, v46
	v_lshl_add_u32 v182, v64, 1, v182
	s_and_b64 s[40:41], s[40:41], s[38:39]
	s_mov_b64 s[4:5], exec
	s_mov_b64 exec, s[40:41]
	global_load_dwordx4 v[124:127], v182, s[34:35]
	s_mov_b64 exec, s[0:1]
	global_load_dwordx4 v[128:131], v183, s[30:31]
	global_load_dwordx4 v[132:135], v183, s[30:31] offset:16
	s_mov_b64 exec, s[4:5]
	global_load_dword v136, v[180:181], off
	global_load_dword v137, v[180:181], off offset:256
	global_load_dword v138, v[180:181], off offset:512
	global_load_dword v139, v[180:181], off offset:768
	global_load_dword v140, v[180:181], off offset:1024
	global_load_dword v141, v[180:181], off offset:1280
	global_load_dword v142, v[180:181], off offset:1536
	global_load_dword v143, v[180:181], off offset:1792
	global_load_dword v150, v[180:181], off offset:128
	global_load_dword v151, v[180:181], off offset:384
	global_load_dword v152, v[180:181], off offset:640
	global_load_dword v153, v[180:181], off offset:896
	global_load_dword v154, v[180:181], off offset:1152
	global_load_dword v155, v[180:181], off offset:1408
	global_load_dword v156, v[180:181], off offset:1664
	global_load_dword v157, v[180:181], off offset:1920
	s_waitcnt vmcnt(19)
	s_mov_b64 s[4:5], exec
	s_mov_b64 exec, s[0:1]
	v_cvt_pk_bf16_f32 v96, v100, v101
	v_cvt_pk_bf16_f32 v97, v102, v103
	v_cvt_pk_bf16_f32 v98, v104, v105
	v_cvt_pk_bf16_f32 v99, v106, v107
	s_mov_b64 exec, s[4:5]
	v_cvt_pk_bf16_f32 v158, v108, v109
	v_cvt_pk_bf16_f32 v159, v110, v111
	v_cvt_pk_bf16_f32 v160, v112, v113
	v_cvt_pk_bf16_f32 v161, v114, v115
	v_cvt_pk_bf16_f32 v176, v116, v117
	v_cvt_pk_bf16_f32 v177, v118, v119
	v_cvt_pk_bf16_f32 v178, v120, v121
	v_cvt_pk_bf16_f32 v179, v122, v123
	s_nop 1
	v_mfma_f32_32x32x16_bf16 v[16:31], v[96:99], v[158:161], v[16:31]
	v_mfma_f32_32x32x16_bf16 v[0:15], v[96:99], v[176:179], v[0:15]
	v_add_u32_e32 v64, 128, v92
	v_lshlrev_b32_e32 v183, 2, v64
	v_lshlrev_b32_e32 v64, 8, v64
	v_lshl_add_u64 v[180:181], v[64:65], 0, v[36:37]
	v_mov_b32_e32 v96, 0
	v_mov_b32_e32 v97, 0
	v_mov_b32_e32 v98, 0
	v_mov_b32_e32 v99, 0
	v_add_u32_e32 v182, 2, v93
	v_cmp_gt_i32_e64 s[40:41], s80, v182
	v_add_u32_e32 v182, s44, v182
	v_mul_u32_u24_e32 v182, s66, v182
	v_add_u32_e32 v64, 0, v46
	v_lshl_add_u32 v182, v64, 1, v182
	s_and_b64 s[40:41], s[40:41], s[38:39]
	s_mov_b64 s[4:5], exec
	s_mov_b64 exec, s[40:41]
	global_load_dwordx4 v[96:99], v182, s[34:35]
	s_mov_b64 exec, s[0:1]
	global_load_dwordx4 v[100:103], v183, s[30:31]
	global_load_dwordx4 v[104:107], v183, s[30:31] offset:16
	s_mov_b64 exec, s[4:5]
	global_load_dword v108, v[180:181], off
	global_load_dword v109, v[180:181], off offset:256
	global_load_dword v110, v[180:181], off offset:512
	global_load_dword v111, v[180:181], off offset:768
	global_load_dword v112, v[180:181], off offset:1024
	global_load_dword v113, v[180:181], off offset:1280
	global_load_dword v114, v[180:181], off offset:1536
	global_load_dword v115, v[180:181], off offset:1792
	global_load_dword v116, v[180:181], off offset:128
	global_load_dword v117, v[180:181], off offset:384
	global_load_dword v118, v[180:181], off offset:640
	global_load_dword v119, v[180:181], off offset:896
	global_load_dword v120, v[180:181], off offset:1152
	global_load_dword v121, v[180:181], off offset:1408
	global_load_dword v122, v[180:181], off offset:1664
	global_load_dword v123, v[180:181], off offset:1920
	s_waitcnt vmcnt(19)
	s_mov_b64 s[4:5], exec
	s_mov_b64 exec, s[0:1]
	v_cvt_pk_bf16_f32 v124, v128, v129
	v_cvt_pk_bf16_f32 v125, v130, v131
	v_cvt_pk_bf16_f32 v126, v132, v133
	v_cvt_pk_bf16_f32 v127, v134, v135
	s_mov_b64 exec, s[4:5]
	v_cvt_pk_bf16_f32 v158, v136, v137
	v_cvt_pk_bf16_f32 v159, v138, v139
	v_cvt_pk_bf16_f32 v160, v140, v141
	v_cvt_pk_bf16_f32 v161, v142, v143
	v_cvt_pk_bf16_f32 v176, v150, v151
	v_cvt_pk_bf16_f32 v177, v152, v153
	v_cvt_pk_bf16_f32 v178, v154, v155
	v_cvt_pk_bf16_f32 v179, v156, v157
	s_nop 1
	v_mfma_f32_32x32x16_bf16 v[16:31], v[124:127], v[158:161], v[16:31]
	v_mfma_f32_32x32x16_bf16 v[0:15], v[124:127], v[176:179], v[0:15]
	v_add_u32_e32 v64, 144, v92
	v_lshlrev_b32_e32 v183, 2, v64
	v_lshlrev_b32_e32 v64, 8, v64
	v_lshl_add_u64 v[180:181], v[64:65], 0, v[36:37]
	v_mov_b32_e32 v124, 0
	v_mov_b32_e32 v125, 0
	v_mov_b32_e32 v126, 0
	v_mov_b32_e32 v127, 0
	v_add_u32_e32 v182, 2, v93
	v_cmp_gt_i32_e64 s[40:41], s80, v182
	v_add_u32_e32 v182, s44, v182
	v_mul_u32_u24_e32 v182, s66, v182
	v_add_u32_e32 v64, 16, v46
	v_lshl_add_u32 v182, v64, 1, v182
	s_and_b64 s[40:41], s[40:41], s[38:39]
	s_mov_b64 s[4:5], exec
	s_mov_b64 exec, s[40:41]
	global_load_dwordx4 v[124:127], v182, s[34:35]
	s_mov_b64 exec, s[0:1]
	global_load_dwordx4 v[128:131], v183, s[30:31]
	global_load_dwordx4 v[132:135], v183, s[30:31] offset:16
	s_mov_b64 exec, s[4:5]
	global_load_dword v136, v[180:181], off
	global_load_dword v137, v[180:181], off offset:256
	global_load_dword v138, v[180:181], off offset:512
	global_load_dword v139, v[180:181], off offset:768
	global_load_dword v140, v[180:181], off offset:1024
	global_load_dword v141, v[180:181], off offset:1280
	global_load_dword v142, v[180:181], off offset:1536
	global_load_dword v143, v[180:181], off offset:1792
	global_load_dword v150, v[180:181], off offset:128
	global_load_dword v151, v[180:181], off offset:384
	global_load_dword v152, v[180:181], off offset:640
	global_load_dword v153, v[180:181], off offset:896
	global_load_dword v154, v[180:181], off offset:1152
	global_load_dword v155, v[180:181], off offset:1408
	global_load_dword v156, v[180:181], off offset:1664
	global_load_dword v157, v[180:181], off offset:1920
	s_waitcnt vmcnt(19)
	s_mov_b64 s[4:5], exec
	s_mov_b64 exec, s[0:1]
	v_cvt_pk_bf16_f32 v96, v100, v101
	v_cvt_pk_bf16_f32 v97, v102, v103
	v_cvt_pk_bf16_f32 v98, v104, v105
	v_cvt_pk_bf16_f32 v99, v106, v107
	s_mov_b64 exec, s[4:5]
	v_cvt_pk_bf16_f32 v158, v108, v109
	v_cvt_pk_bf16_f32 v159, v110, v111
	v_cvt_pk_bf16_f32 v160, v112, v113
	v_cvt_pk_bf16_f32 v161, v114, v115
	v_cvt_pk_bf16_f32 v176, v116, v117
	v_cvt_pk_bf16_f32 v177, v118, v119
	v_cvt_pk_bf16_f32 v178, v120, v121
	v_cvt_pk_bf16_f32 v179, v122, v123
	s_nop 1
	v_mfma_f32_32x32x16_bf16 v[16:31], v[96:99], v[158:161], v[16:31]
	v_mfma_f32_32x32x16_bf16 v[0:15], v[96:99], v[176:179], v[0:15]
	v_add_u32_e32 v64, 160, v92
	v_lshlrev_b32_e32 v183, 2, v64
	v_lshlrev_b32_e32 v64, 8, v64
	v_lshl_add_u64 v[180:181], v[64:65], 0, v[36:37]
	v_mov_b32_e32 v96, 0
	v_mov_b32_e32 v97, 0
	v_mov_b32_e32 v98, 0
	v_mov_b32_e32 v99, 0
	v_add_u32_e32 v182, 2, v93
	v_cmp_gt_i32_e64 s[40:41], s80, v182
	v_add_u32_e32 v182, s44, v182
	v_mul_u32_u24_e32 v182, s66, v182
	v_add_u32_e32 v64, 32, v46
	v_lshl_add_u32 v182, v64, 1, v182
	s_and_b64 s[40:41], s[40:41], s[38:39]
	s_mov_b64 s[4:5], exec
	s_mov_b64 exec, s[40:41]
	global_load_dwordx4 v[96:99], v182, s[34:35]
	s_mov_b64 exec, s[0:1]
	global_load_dwordx4 v[100:103], v183, s[30:31]
	global_load_dwordx4 v[104:107], v183, s[30:31] offset:16
	s_mov_b64 exec, s[4:5]
	global_load_dword v108, v[180:181], off
	global_load_dword v109, v[180:181], off offset:256
	global_load_dword v110, v[180:181], off offset:512
	global_load_dword v111, v[180:181], off offset:768
	global_load_dword v112, v[180:181], off offset:1024
	global_load_dword v113, v[180:181], off offset:1280
	global_load_dword v114, v[180:181], off offset:1536
	global_load_dword v115, v[180:181], off offset:1792
	global_load_dword v116, v[180:181], off offset:128
	global_load_dword v117, v[180:181], off offset:384
	global_load_dword v118, v[180:181], off offset:640
	global_load_dword v119, v[180:181], off offset:896
	global_load_dword v120, v[180:181], off offset:1152
	global_load_dword v121, v[180:181], off offset:1408
	global_load_dword v122, v[180:181], off offset:1664
	global_load_dword v123, v[180:181], off offset:1920
	s_waitcnt vmcnt(19)
	s_mov_b64 s[4:5], exec
	s_mov_b64 exec, s[0:1]
	v_cvt_pk_bf16_f32 v124, v128, v129
	v_cvt_pk_bf16_f32 v125, v130, v131
	v_cvt_pk_bf16_f32 v126, v132, v133
	v_cvt_pk_bf16_f32 v127, v134, v135
	s_mov_b64 exec, s[4:5]
	v_cvt_pk_bf16_f32 v158, v136, v137
	v_cvt_pk_bf16_f32 v159, v138, v139
	v_cvt_pk_bf16_f32 v160, v140, v141
	v_cvt_pk_bf16_f32 v161, v142, v143
	v_cvt_pk_bf16_f32 v176, v150, v151
	v_cvt_pk_bf16_f32 v177, v152, v153
	v_cvt_pk_bf16_f32 v178, v154, v155
	v_cvt_pk_bf16_f32 v179, v156, v157
	s_nop 1
	v_mfma_f32_32x32x16_bf16 v[16:31], v[124:127], v[158:161], v[16:31]
	v_mfma_f32_32x32x16_bf16 v[0:15], v[124:127], v[176:179], v[0:15]
	v_add_u32_e32 v64, 176, v92
	v_lshlrev_b32_e32 v183, 2, v64
	v_lshlrev_b32_e32 v64, 8, v64
	v_lshl_add_u64 v[180:181], v[64:65], 0, v[36:37]
	v_mov_b32_e32 v124, 0
	v_mov_b32_e32 v125, 0
	v_mov_b32_e32 v126, 0
	v_mov_b32_e32 v127, 0
	v_add_u32_e32 v182, 2, v93
	v_cmp_gt_i32_e64 s[40:41], s80, v182
	v_add_u32_e32 v182, s44, v182
	v_mul_u32_u24_e32 v182, s66, v182
	v_add_u32_e32 v64, 48, v46
	v_lshl_add_u32 v182, v64, 1, v182
	s_and_b64 s[40:41], s[40:41], s[38:39]
	s_mov_b64 s[4:5], exec
	s_mov_b64 exec, s[40:41]
	global_load_dwordx4 v[124:127], v182, s[34:35]
	s_mov_b64 exec, s[0:1]
	global_load_dwordx4 v[128:131], v183, s[30:31]
	global_load_dwordx4 v[132:135], v183, s[30:31] offset:16
	s_mov_b64 exec, s[4:5]
	global_load_dword v136, v[180:181], off
	global_load_dword v137, v[180:181], off offset:256
	global_load_dword v138, v[180:181], off offset:512
	global_load_dword v139, v[180:181], off offset:768
	global_load_dword v140, v[180:181], off offset:1024
	global_load_dword v141, v[180:181], off offset:1280
	global_load_dword v142, v[180:181], off offset:1536
	global_load_dword v143, v[180:181], off offset:1792
	global_load_dword v150, v[180:181], off offset:128
	global_load_dword v151, v[180:181], off offset:384
	global_load_dword v152, v[180:181], off offset:640
	global_load_dword v153, v[180:181], off offset:896
	global_load_dword v154, v[180:181], off offset:1152
	global_load_dword v155, v[180:181], off offset:1408
	global_load_dword v156, v[180:181], off offset:1664
	global_load_dword v157, v[180:181], off offset:1920
	s_waitcnt vmcnt(19)
	s_mov_b64 s[4:5], exec
	s_mov_b64 exec, s[0:1]
	v_cvt_pk_bf16_f32 v96, v100, v101
	v_cvt_pk_bf16_f32 v97, v102, v103
	v_cvt_pk_bf16_f32 v98, v104, v105
	v_cvt_pk_bf16_f32 v99, v106, v107
	s_mov_b64 exec, s[4:5]
	v_cvt_pk_bf16_f32 v158, v108, v109
	v_cvt_pk_bf16_f32 v159, v110, v111
	v_cvt_pk_bf16_f32 v160, v112, v113
	v_cvt_pk_bf16_f32 v161, v114, v115
	v_cvt_pk_bf16_f32 v176, v116, v117
	v_cvt_pk_bf16_f32 v177, v118, v119
	v_cvt_pk_bf16_f32 v178, v120, v121
	v_cvt_pk_bf16_f32 v179, v122, v123
	s_nop 1
	v_mfma_f32_32x32x16_bf16 v[16:31], v[96:99], v[158:161], v[16:31]
	v_mfma_f32_32x32x16_bf16 v[0:15], v[96:99], v[176:179], v[0:15]
	v_add_u32_e32 v64, 192, v92
	v_lshlrev_b32_e32 v183, 2, v64
	v_lshlrev_b32_e32 v64, 8, v64
	v_lshl_add_u64 v[180:181], v[64:65], 0, v[36:37]
	v_mov_b32_e32 v96, 0
	v_mov_b32_e32 v97, 0
	v_mov_b32_e32 v98, 0
	v_mov_b32_e32 v99, 0
	v_add_u32_e32 v182, 3, v93
	v_cmp_gt_i32_e64 s[40:41], s80, v182
	v_add_u32_e32 v182, s44, v182
	v_mul_u32_u24_e32 v182, s66, v182
	v_add_u32_e32 v64, 0, v46
	v_lshl_add_u32 v182, v64, 1, v182
	s_and_b64 s[40:41], s[40:41], s[38:39]
	s_mov_b64 s[4:5], exec
	s_mov_b64 exec, s[40:41]
	global_load_dwordx4 v[96:99], v182, s[34:35]
	s_mov_b64 exec, s[0:1]
	global_load_dwordx4 v[100:103], v183, s[30:31]
	global_load_dwordx4 v[104:107], v183, s[30:31] offset:16
	s_mov_b64 exec, s[4:5]
	global_load_dword v108, v[180:181], off
	global_load_dword v109, v[180:181], off offset:256
	global_load_dword v110, v[180:181], off offset:512
	global_load_dword v111, v[180:181], off offset:768
	global_load_dword v112, v[180:181], off offset:1024
	global_load_dword v113, v[180:181], off offset:1280
	global_load_dword v114, v[180:181], off offset:1536
	global_load_dword v115, v[180:181], off offset:1792
	global_load_dword v116, v[180:181], off offset:128
	global_load_dword v117, v[180:181], off offset:384
	global_load_dword v118, v[180:181], off offset:640
	global_load_dword v119, v[180:181], off offset:896
	global_load_dword v120, v[180:181], off offset:1152
	global_load_dword v121, v[180:181], off offset:1408
	global_load_dword v122, v[180:181], off offset:1664
	global_load_dword v123, v[180:181], off offset:1920
	s_waitcnt vmcnt(19)
	s_mov_b64 s[4:5], exec
	s_mov_b64 exec, s[0:1]
	v_cvt_pk_bf16_f32 v124, v128, v129
	v_cvt_pk_bf16_f32 v125, v130, v131
	v_cvt_pk_bf16_f32 v126, v132, v133
	v_cvt_pk_bf16_f32 v127, v134, v135
	s_mov_b64 exec, s[4:5]
	v_cvt_pk_bf16_f32 v158, v136, v137
	v_cvt_pk_bf16_f32 v159, v138, v139
	v_cvt_pk_bf16_f32 v160, v140, v141
	v_cvt_pk_bf16_f32 v161, v142, v143
	v_cvt_pk_bf16_f32 v176, v150, v151
	v_cvt_pk_bf16_f32 v177, v152, v153
	v_cvt_pk_bf16_f32 v178, v154, v155
	v_cvt_pk_bf16_f32 v179, v156, v157
	s_nop 1
	v_mfma_f32_32x32x16_bf16 v[16:31], v[124:127], v[158:161], v[16:31]
	v_mfma_f32_32x32x16_bf16 v[0:15], v[124:127], v[176:179], v[0:15]
	v_add_u32_e32 v64, 208, v92
	v_lshlrev_b32_e32 v183, 2, v64
	v_lshlrev_b32_e32 v64, 8, v64
	v_lshl_add_u64 v[180:181], v[64:65], 0, v[36:37]
	v_mov_b32_e32 v124, 0
	v_mov_b32_e32 v125, 0
	v_mov_b32_e32 v126, 0
	v_mov_b32_e32 v127, 0
	v_add_u32_e32 v182, 3, v93
	v_cmp_gt_i32_e64 s[40:41], s80, v182
	v_add_u32_e32 v182, s44, v182
	v_mul_u32_u24_e32 v182, s66, v182
	v_add_u32_e32 v64, 16, v46
	v_lshl_add_u32 v182, v64, 1, v182
	s_and_b64 s[40:41], s[40:41], s[38:39]
	s_mov_b64 s[4:5], exec
	s_mov_b64 exec, s[40:41]
	global_load_dwordx4 v[124:127], v182, s[34:35]
	s_mov_b64 exec, s[0:1]
	global_load_dwordx4 v[128:131], v183, s[30:31]
	global_load_dwordx4 v[132:135], v183, s[30:31] offset:16
	s_mov_b64 exec, s[4:5]
	global_load_dword v136, v[180:181], off
	global_load_dword v137, v[180:181], off offset:256
	global_load_dword v138, v[180:181], off offset:512
	global_load_dword v139, v[180:181], off offset:768
	global_load_dword v140, v[180:181], off offset:1024
	global_load_dword v141, v[180:181], off offset:1280
	global_load_dword v142, v[180:181], off offset:1536
	global_load_dword v143, v[180:181], off offset:1792
	global_load_dword v150, v[180:181], off offset:128
	global_load_dword v151, v[180:181], off offset:384
	global_load_dword v152, v[180:181], off offset:640
	global_load_dword v153, v[180:181], off offset:896
	global_load_dword v154, v[180:181], off offset:1152
	global_load_dword v155, v[180:181], off offset:1408
	global_load_dword v156, v[180:181], off offset:1664
	global_load_dword v157, v[180:181], off offset:1920
	s_waitcnt vmcnt(19)
	s_mov_b64 s[4:5], exec
	s_mov_b64 exec, s[0:1]
	v_cvt_pk_bf16_f32 v96, v100, v101
	v_cvt_pk_bf16_f32 v97, v102, v103
	v_cvt_pk_bf16_f32 v98, v104, v105
	v_cvt_pk_bf16_f32 v99, v106, v107
	s_mov_b64 exec, s[4:5]
	v_cvt_pk_bf16_f32 v158, v108, v109
	v_cvt_pk_bf16_f32 v159, v110, v111
	v_cvt_pk_bf16_f32 v160, v112, v113
	v_cvt_pk_bf16_f32 v161, v114, v115
	v_cvt_pk_bf16_f32 v176, v116, v117
	v_cvt_pk_bf16_f32 v177, v118, v119
	v_cvt_pk_bf16_f32 v178, v120, v121
	v_cvt_pk_bf16_f32 v179, v122, v123
	s_nop 1
	v_mfma_f32_32x32x16_bf16 v[16:31], v[96:99], v[158:161], v[16:31]
	v_mfma_f32_32x32x16_bf16 v[0:15], v[96:99], v[176:179], v[0:15]
	v_add_u32_e32 v64, 224, v92
	v_lshlrev_b32_e32 v183, 2, v64
	v_lshlrev_b32_e32 v64, 8, v64
	v_lshl_add_u64 v[180:181], v[64:65], 0, v[36:37]
	v_mov_b32_e32 v96, 0
	v_mov_b32_e32 v97, 0
	v_mov_b32_e32 v98, 0
	v_mov_b32_e32 v99, 0
	v_add_u32_e32 v182, 3, v93
	v_cmp_gt_i32_e64 s[40:41], s80, v182
	v_add_u32_e32 v182, s44, v182
	v_mul_u32_u24_e32 v182, s66, v182
	v_add_u32_e32 v64, 32, v46
	v_lshl_add_u32 v182, v64, 1, v182
	s_and_b64 s[40:41], s[40:41], s[38:39]
	s_mov_b64 s[4:5], exec
	s_mov_b64 exec, s[40:41]
	global_load_dwordx4 v[96:99], v182, s[34:35]
	s_mov_b64 exec, s[0:1]
	global_load_dwordx4 v[100:103], v183, s[30:31]
	global_load_dwordx4 v[104:107], v183, s[30:31] offset:16
	s_mov_b64 exec, s[4:5]
	global_load_dword v108, v[180:181], off
	global_load_dword v109, v[180:181], off offset:256
	global_load_dword v110, v[180:181], off offset:512
	global_load_dword v111, v[180:181], off offset:768
	global_load_dword v112, v[180:181], off offset:1024
	global_load_dword v113, v[180:181], off offset:1280
	global_load_dword v114, v[180:181], off offset:1536
	global_load_dword v115, v[180:181], off offset:1792
	global_load_dword v116, v[180:181], off offset:128
	global_load_dword v117, v[180:181], off offset:384
	global_load_dword v118, v[180:181], off offset:640
	global_load_dword v119, v[180:181], off offset:896
	global_load_dword v120, v[180:181], off offset:1152
	global_load_dword v121, v[180:181], off offset:1408
	global_load_dword v122, v[180:181], off offset:1664
	global_load_dword v123, v[180:181], off offset:1920
	s_waitcnt vmcnt(19)
	s_mov_b64 s[4:5], exec
	s_mov_b64 exec, s[0:1]
	v_cvt_pk_bf16_f32 v124, v128, v129
	v_cvt_pk_bf16_f32 v125, v130, v131
	v_cvt_pk_bf16_f32 v126, v132, v133
	v_cvt_pk_bf16_f32 v127, v134, v135
	s_mov_b64 exec, s[4:5]
	v_cvt_pk_bf16_f32 v158, v136, v137
	v_cvt_pk_bf16_f32 v159, v138, v139
	v_cvt_pk_bf16_f32 v160, v140, v141
	v_cvt_pk_bf16_f32 v161, v142, v143
	v_cvt_pk_bf16_f32 v176, v150, v151
	v_cvt_pk_bf16_f32 v177, v152, v153
	v_cvt_pk_bf16_f32 v178, v154, v155
	v_cvt_pk_bf16_f32 v179, v156, v157
	s_nop 1
	v_mfma_f32_32x32x16_bf16 v[16:31], v[124:127], v[158:161], v[16:31]
	v_mfma_f32_32x32x16_bf16 v[0:15], v[124:127], v[176:179], v[0:15]
	v_add_u32_e32 v64, 240, v92
	v_lshlrev_b32_e32 v183, 2, v64
	v_lshlrev_b32_e32 v64, 8, v64
	v_lshl_add_u64 v[180:181], v[64:65], 0, v[36:37]
	v_mov_b32_e32 v124, 0
	v_mov_b32_e32 v125, 0
	v_mov_b32_e32 v126, 0
	v_mov_b32_e32 v127, 0
	v_add_u32_e32 v182, 3, v93
	v_cmp_gt_i32_e64 s[40:41], s80, v182
	v_add_u32_e32 v182, s44, v182
	v_mul_u32_u24_e32 v182, s66, v182
	v_add_u32_e32 v64, 48, v46
	v_lshl_add_u32 v182, v64, 1, v182
	s_and_b64 s[40:41], s[40:41], s[38:39]
	s_mov_b64 s[4:5], exec
	s_mov_b64 exec, s[40:41]
	global_load_dwordx4 v[124:127], v182, s[34:35]
	s_mov_b64 exec, s[0:1]
	global_load_dwordx4 v[128:131], v183, s[30:31]
	global_load_dwordx4 v[132:135], v183, s[30:31] offset:16
	s_mov_b64 exec, s[4:5]
	global_load_dword v136, v[180:181], off
	global_load_dword v137, v[180:181], off offset:256
	global_load_dword v138, v[180:181], off offset:512
	global_load_dword v139, v[180:181], off offset:768
	global_load_dword v140, v[180:181], off offset:1024
	global_load_dword v141, v[180:181], off offset:1280
	global_load_dword v142, v[180:181], off offset:1536
	global_load_dword v143, v[180:181], off offset:1792
	global_load_dword v150, v[180:181], off offset:128
	global_load_dword v151, v[180:181], off offset:384
	global_load_dword v152, v[180:181], off offset:640
	global_load_dword v153, v[180:181], off offset:896
	global_load_dword v154, v[180:181], off offset:1152
	global_load_dword v155, v[180:181], off offset:1408
	global_load_dword v156, v[180:181], off offset:1664
	global_load_dword v157, v[180:181], off offset:1920
	s_waitcnt vmcnt(19)
	s_mov_b64 s[4:5], exec
	s_mov_b64 exec, s[0:1]
	v_cvt_pk_bf16_f32 v96, v100, v101
	v_cvt_pk_bf16_f32 v97, v102, v103
	v_cvt_pk_bf16_f32 v98, v104, v105
	v_cvt_pk_bf16_f32 v99, v106, v107
	s_mov_b64 exec, s[4:5]
	v_cvt_pk_bf16_f32 v158, v108, v109
	v_cvt_pk_bf16_f32 v159, v110, v111
	v_cvt_pk_bf16_f32 v160, v112, v113
	v_cvt_pk_bf16_f32 v161, v114, v115
	v_cvt_pk_bf16_f32 v176, v116, v117
	v_cvt_pk_bf16_f32 v177, v118, v119
	v_cvt_pk_bf16_f32 v178, v120, v121
	v_cvt_pk_bf16_f32 v179, v122, v123
	s_nop 1
	v_mfma_f32_32x32x16_bf16 v[16:31], v[96:99], v[158:161], v[16:31]
	v_mfma_f32_32x32x16_bf16 v[0:15], v[96:99], v[176:179], v[0:15]
	s_waitcnt vmcnt(0)
	s_mov_b64 s[4:5], exec
	s_mov_b64 exec, s[0:1]
	v_cvt_pk_bf16_f32 v124, v128, v129
	v_cvt_pk_bf16_f32 v125, v130, v131
	v_cvt_pk_bf16_f32 v126, v132, v133
	v_cvt_pk_bf16_f32 v127, v134, v135
	s_mov_b64 exec, s[4:5]
	v_cvt_pk_bf16_f32 v158, v136, v137
	v_cvt_pk_bf16_f32 v159, v138, v139
	v_cvt_pk_bf16_f32 v160, v140, v141
	v_cvt_pk_bf16_f32 v161, v142, v143
	v_cvt_pk_bf16_f32 v176, v150, v151
	v_cvt_pk_bf16_f32 v177, v152, v153
	v_cvt_pk_bf16_f32 v178, v154, v155
	v_cvt_pk_bf16_f32 v179, v156, v157
	s_nop 1
	v_mfma_f32_32x32x16_bf16 v[16:31], v[124:127], v[158:161], v[16:31]
	v_mfma_f32_32x32x16_bf16 v[0:15], v[124:127], v[176:179], v[0:15]
	s_branch .LBB0_516
